# SGU: in-place u read and written with 16 bytes per lane (adjacent channel blocks paired by v_permlane16_swap) instead of 8
# speedup vs baseline: 1.0066x; 1.0044x over previous
.LBB0_696:
	s_and_b32 s6, s3, 0xffffff80
	s_and_b32 s0, s13, 3
	v_add_u32_e32 v0, s6, v96
	s_mov_b32 s1, s9
	s_lshl_b32 s8, s0, 9
	s_lshl_b32 s4, s0, 10
	v_add_u32_e32 v6, s6, v97
	v_add_u32_e32 v8, s6, v98
	v_add_u32_e32 v10, s6, v99
	v_add_u32_e32 v12, s6, v100
	v_add_u32_e32 v14, s6, v101
	v_add_u32_e32 v16, s6, v102
	v_add_u32_e32 v34, s6, v103
	s_lshl_b32 s0, s0, 7
	v_ashrrev_i32_e32 v1, 31, v0
	s_mov_b32 s5, s9
	v_ashrrev_i32_e32 v7, 31, v6
	v_ashrrev_i32_e32 v9, 31, v8
	v_ashrrev_i32_e32 v11, 31, v10
	v_ashrrev_i32_e32 v13, 31, v12
	v_ashrrev_i32_e32 v15, 31, v14
	v_ashrrev_i32_e32 v17, 31, v16
	v_ashrrev_i32_e32 v35, 31, v34
	v_lshl_add_u64 v[38:39], s[0:1], 0, v[84:85]
	v_lshlrev_b64 v[40:41], 11, v[0:1]
	v_lshlrev_b64 v[0:1], 2, v[0:1]
	v_lshl_add_u64 v[36:37], v[78:79], 0, s[8:9]
	v_lshl_add_u64 v[2:3], v[80:81], 0, s[4:5]
	v_lshlrev_b64 v[42:43], 11, v[6:7]
	v_lshlrev_b64 v[6:7], 2, v[6:7]
	v_lshlrev_b64 v[44:45], 11, v[8:9]
	v_lshlrev_b64 v[8:9], 2, v[8:9]
	v_lshlrev_b64 v[46:47], 11, v[10:11]
	v_lshlrev_b64 v[10:11], 2, v[10:11]
	v_lshlrev_b64 v[48:49], 11, v[12:13]
	v_lshlrev_b64 v[12:13], 2, v[12:13]
	v_lshlrev_b64 v[50:51], 11, v[14:15]
	v_lshlrev_b64 v[52:53], 11, v[16:17]
	v_lshlrev_b64 v[54:55], 11, v[34:35]
	v_lshlrev_b64 v[34:35], 2, v[34:35]
	v_lshlrev_b64 v[38:39], 9, v[38:39]
	v_lshl_add_u64 v[56:57], s[52:53], 0, v[0:1]
	s_barrier
	v_lshl_add_u64 v[4:5], v[82:83], 0, s[4:5]
	global_load_dwordx4 v[148:151], v[2:3], off offset:16
	global_load_dwordx4 v[144:147], v[2:3], off
	global_load_dwordx4 v[156:159], v[4:5], off offset:16
	global_load_dwordx4 v[152:155], v[4:5], off
	v_lshl_add_u64 v[40:41], v[36:37], 0, v[40:41]
	v_lshl_add_u64 v[58:59], s[14:15], 0, v[0:1]
	v_lshl_add_u64 v[42:43], v[36:37], 0, v[42:43]
	v_lshl_add_u64 v[60:61], s[52:53], 0, v[6:7]
	v_lshl_add_u64 v[62:63], s[14:15], 0, v[6:7]
	v_lshl_add_u64 v[44:45], v[36:37], 0, v[44:45]
	v_lshl_add_u64 v[64:65], s[52:53], 0, v[8:9]
	v_lshl_add_u64 v[66:67], s[14:15], 0, v[8:9]
	v_lshl_add_u64 v[46:47], v[36:37], 0, v[46:47]
	v_lshl_add_u64 v[68:69], s[52:53], 0, v[10:11]
	v_lshl_add_u64 v[70:71], s[14:15], 0, v[10:11]
	v_lshl_add_u64 v[48:49], v[36:37], 0, v[48:49]
	v_lshl_add_u64 v[72:73], s[52:53], 0, v[12:13]
	v_lshl_add_u64 v[74:75], s[14:15], 0, v[12:13]
	v_lshl_add_u64 v[50:51], v[36:37], 0, v[50:51]
	v_lshl_add_u64 v[12:13], v[36:37], 0, v[52:53]
	v_lshl_add_u64 v[6:7], v[36:37], 0, v[54:55]
	v_lshl_add_u64 v[8:9], s[52:53], 0, v[34:35]
	v_lshl_add_u64 v[10:11], s[14:15], 0, v[34:35]
	v_lshl_add_u64 v[0:1], v[86:87], 0, v[38:39]
	v_lshlrev_b64 v[14:15], 2, v[14:15]
	v_lshl_add_u64 v[90:91], s[52:53], 0, v[14:15]
	v_lshl_add_u64 v[92:93], s[14:15], 0, v[14:15]
	v_lshlrev_b64 v[16:17], 2, v[16:17]
	v_lshl_add_u64 v[14:15], s[52:53], 0, v[16:17]
	v_lshl_add_u64 v[16:17], s[14:15], 0, v[16:17]
	s_add_i32 s3, s3, s11
	global_load_dword v193, v[56:57], off
	global_load_dword v192, v[58:59], off
	global_load_dwordx4 v[160:163], v[40:41], off
	global_load_dword v195, v[60:61], off
	global_load_dword v194, v[62:63], off
	global_load_dwordx4 v[164:167], v[42:43], off
	global_load_dword v197, v[64:65], off
	global_load_dword v196, v[66:67], off
	global_load_dwordx4 v[168:171], v[44:45], off
	global_load_dword v199, v[68:69], off
	global_load_dword v198, v[70:71], off
	global_load_dwordx4 v[172:175], v[46:47], off
	global_load_dword v201, v[72:73], off
	global_load_dword v200, v[74:75], off
	global_load_dwordx4 v[176:179], v[48:49], off
	global_load_dword v203, v[90:91], off
	global_load_dword v202, v[92:93], off
	global_load_dwordx4 v[180:183], v[50:51], off
	global_load_dword v205, v[14:15], off
	global_load_dword v204, v[16:17], off
	global_load_dwordx4 v[184:187], v[12:13], off
	global_load_dword v207, v[8:9], off
	global_load_dword v206, v[10:11], off
	global_load_dwordx4 v[188:191], v[6:7], off
	global_load_dwordx4 v[208:211], v[0:1], off
	global_load_dwordx4 v[212:215], v[0:1], off offset:64
	global_load_dwordx4 v[216:219], v[0:1], off offset:128
	global_load_dwordx4 v[220:223], v[0:1], off offset:192
	global_load_dwordx4 v[224:227], v[0:1], off offset:256
	global_load_dwordx4 v[232:235], v[0:1], off offset:320
	global_load_dwordx4 v[236:239], v[0:1], off offset:384
	global_load_dwordx4 v[240:243], v[0:1], off offset:448
	s_waitcnt vmcnt(29)
	v_pk_mul_f32 v[192:193], v[192:193], s[10:11] op_sel_hi:[1,0]
	s_nop 0
	v_fma_f32 v192, -v193, v193, v192
	v_add_f32_e32 v192, 0x358637bd, v192
	v_rsq_f32_e32 v192, v192
	v_lshlrev_b32_e32 v22, 16, v160
	v_and_b32_e32 v23, 0xffff0000, v160
	v_lshlrev_b32_e32 v24, 16, v161
	v_and_b32_e32 v25, 0xffff0000, v161
	v_lshlrev_b32_e32 v26, 16, v162
	v_and_b32_e32 v27, 0xffff0000, v162
	v_lshlrev_b32_e32 v28, 16, v163
	v_and_b32_e32 v29, 0xffff0000, v163
	v_sub_f32_e32 v22, v22, v193
	v_sub_f32_e32 v23, v23, v193
	v_sub_f32_e32 v24, v24, v193
	v_sub_f32_e32 v25, v25, v193
	v_sub_f32_e32 v26, v26, v193
	v_sub_f32_e32 v27, v27, v193
	v_sub_f32_e32 v28, v28, v193
	v_sub_f32_e32 v29, v29, v193
	v_mul_f32_e32 v22, v22, v192
	v_mul_f32_e32 v23, v23, v192
	v_mul_f32_e32 v24, v24, v192
	v_mul_f32_e32 v25, v25, v192
	v_mul_f32_e32 v26, v26, v192
	v_mul_f32_e32 v27, v27, v192
	v_mul_f32_e32 v28, v28, v192
	v_mul_f32_e32 v29, v29, v192
	v_fma_f32 v22, v144, v22, v152
	v_fma_f32 v23, v145, v23, v153
	v_fma_f32 v24, v146, v24, v154
	v_fma_f32 v25, v147, v25, v155
	v_fma_f32 v26, v148, v26, v156
	v_fma_f32 v27, v149, v27, v157
	v_fma_f32 v28, v150, v28, v158
	v_fma_f32 v29, v151, v29, v159
	v_cvt_pk_bf16_f32 v18, v22, v23
	v_cvt_pk_bf16_f32 v19, v24, v25
	v_cvt_pk_bf16_f32 v20, v26, v27
	v_cvt_pk_bf16_f32 v21, v28, v29
	ds_write_b128 v105, v[18:21]
	s_waitcnt vmcnt(26)
	v_pk_mul_f32 v[194:195], v[194:195], s[10:11] op_sel_hi:[1,0]
	s_nop 0
	v_fma_f32 v194, -v195, v195, v194
	v_add_f32_e32 v194, 0x358637bd, v194
	v_rsq_f32_e32 v194, v194
	v_lshlrev_b32_e32 v22, 16, v164
	v_and_b32_e32 v23, 0xffff0000, v164
	v_lshlrev_b32_e32 v24, 16, v165
	v_and_b32_e32 v25, 0xffff0000, v165
	v_lshlrev_b32_e32 v26, 16, v166
	v_and_b32_e32 v27, 0xffff0000, v166
	v_lshlrev_b32_e32 v28, 16, v167
	v_and_b32_e32 v29, 0xffff0000, v167
	v_sub_f32_e32 v22, v22, v195
	v_sub_f32_e32 v23, v23, v195
	v_sub_f32_e32 v24, v24, v195
	v_sub_f32_e32 v25, v25, v195
	v_sub_f32_e32 v26, v26, v195
	v_sub_f32_e32 v27, v27, v195
	v_sub_f32_e32 v28, v28, v195
	v_sub_f32_e32 v29, v29, v195
	v_mul_f32_e32 v22, v22, v194
	v_mul_f32_e32 v23, v23, v194
	v_mul_f32_e32 v24, v24, v194
	v_mul_f32_e32 v25, v25, v194
	v_mul_f32_e32 v26, v26, v194
	v_mul_f32_e32 v27, v27, v194
	v_mul_f32_e32 v28, v28, v194
	v_mul_f32_e32 v29, v29, v194
	v_fma_f32 v22, v144, v22, v152
	v_fma_f32 v23, v145, v23, v153
	v_fma_f32 v24, v146, v24, v154
	v_fma_f32 v25, v147, v25, v155
	v_fma_f32 v26, v148, v26, v156
	v_fma_f32 v27, v149, v27, v157
	v_fma_f32 v28, v150, v28, v158
	v_fma_f32 v29, v151, v29, v159
	v_cvt_pk_bf16_f32 v30, v22, v23
	v_cvt_pk_bf16_f32 v31, v24, v25
	v_cvt_pk_bf16_f32 v32, v26, v27
	v_cvt_pk_bf16_f32 v33, v28, v29
	ds_write_b128 v106, v[30:33]
	s_waitcnt vmcnt(23)
	v_pk_mul_f32 v[196:197], v[196:197], s[10:11] op_sel_hi:[1,0]
	s_nop 0
	v_fma_f32 v196, -v197, v197, v196
	v_add_f32_e32 v196, 0x358637bd, v196
	v_rsq_f32_e32 v196, v196
	v_lshlrev_b32_e32 v22, 16, v168
	v_and_b32_e32 v23, 0xffff0000, v168
	v_lshlrev_b32_e32 v24, 16, v169
	v_and_b32_e32 v25, 0xffff0000, v169
	v_lshlrev_b32_e32 v26, 16, v170
	v_and_b32_e32 v27, 0xffff0000, v170
	v_lshlrev_b32_e32 v28, 16, v171
	v_and_b32_e32 v29, 0xffff0000, v171
	v_sub_f32_e32 v22, v22, v197
	v_sub_f32_e32 v23, v23, v197
	v_sub_f32_e32 v24, v24, v197
	v_sub_f32_e32 v25, v25, v197
	v_sub_f32_e32 v26, v26, v197
	v_sub_f32_e32 v27, v27, v197
	v_sub_f32_e32 v28, v28, v197
	v_sub_f32_e32 v29, v29, v197
	v_mul_f32_e32 v22, v22, v196
	v_mul_f32_e32 v23, v23, v196
	v_mul_f32_e32 v24, v24, v196
	v_mul_f32_e32 v25, v25, v196
	v_mul_f32_e32 v26, v26, v196
	v_mul_f32_e32 v27, v27, v196
	v_mul_f32_e32 v28, v28, v196
	v_mul_f32_e32 v29, v29, v196
	v_fma_f32 v22, v144, v22, v152
	v_fma_f32 v23, v145, v23, v153
	v_fma_f32 v24, v146, v24, v154
	v_fma_f32 v25, v147, v25, v155
	v_fma_f32 v26, v148, v26, v156
	v_fma_f32 v27, v149, v27, v157
	v_fma_f32 v28, v150, v28, v158
	v_fma_f32 v29, v151, v29, v159
	v_cvt_pk_bf16_f32 v18, v22, v23
	v_cvt_pk_bf16_f32 v19, v24, v25
	v_cvt_pk_bf16_f32 v20, v26, v27
	v_cvt_pk_bf16_f32 v21, v28, v29
	ds_write_b128 v107, v[18:21]
	s_waitcnt vmcnt(20)
	v_pk_mul_f32 v[198:199], v[198:199], s[10:11] op_sel_hi:[1,0]
	s_nop 0
	v_fma_f32 v198, -v199, v199, v198
	v_add_f32_e32 v198, 0x358637bd, v198
	v_rsq_f32_e32 v198, v198
	v_lshlrev_b32_e32 v22, 16, v172
	v_and_b32_e32 v23, 0xffff0000, v172
	v_lshlrev_b32_e32 v24, 16, v173
	v_and_b32_e32 v25, 0xffff0000, v173
	v_lshlrev_b32_e32 v26, 16, v174
	v_and_b32_e32 v27, 0xffff0000, v174
	v_lshlrev_b32_e32 v28, 16, v175
	v_and_b32_e32 v29, 0xffff0000, v175
	v_sub_f32_e32 v22, v22, v199
	v_sub_f32_e32 v23, v23, v199
	v_sub_f32_e32 v24, v24, v199
	v_sub_f32_e32 v25, v25, v199
	v_sub_f32_e32 v26, v26, v199
	v_sub_f32_e32 v27, v27, v199
	v_sub_f32_e32 v28, v28, v199
	v_sub_f32_e32 v29, v29, v199
	v_mul_f32_e32 v22, v22, v198
	v_mul_f32_e32 v23, v23, v198
	v_mul_f32_e32 v24, v24, v198
	v_mul_f32_e32 v25, v25, v198
	v_mul_f32_e32 v26, v26, v198
	v_mul_f32_e32 v27, v27, v198
	v_mul_f32_e32 v28, v28, v198
	v_mul_f32_e32 v29, v29, v198
	v_fma_f32 v22, v144, v22, v152
	v_fma_f32 v23, v145, v23, v153
	v_fma_f32 v24, v146, v24, v154
	v_fma_f32 v25, v147, v25, v155
	v_fma_f32 v26, v148, v26, v156
	v_fma_f32 v27, v149, v27, v157
	v_fma_f32 v28, v150, v28, v158
	v_fma_f32 v29, v151, v29, v159
	v_cvt_pk_bf16_f32 v30, v22, v23
	v_cvt_pk_bf16_f32 v31, v24, v25
	v_cvt_pk_bf16_f32 v32, v26, v27
	v_cvt_pk_bf16_f32 v33, v28, v29
	ds_write_b128 v108, v[30:33]
	s_waitcnt vmcnt(17)
	v_pk_mul_f32 v[200:201], v[200:201], s[10:11] op_sel_hi:[1,0]
	s_nop 0
	v_fma_f32 v200, -v201, v201, v200
	v_add_f32_e32 v200, 0x358637bd, v200
	v_rsq_f32_e32 v200, v200
	v_lshlrev_b32_e32 v22, 16, v176
	v_and_b32_e32 v23, 0xffff0000, v176
	v_lshlrev_b32_e32 v24, 16, v177
	v_and_b32_e32 v25, 0xffff0000, v177
	v_lshlrev_b32_e32 v26, 16, v178
	v_and_b32_e32 v27, 0xffff0000, v178
	v_lshlrev_b32_e32 v28, 16, v179
	v_and_b32_e32 v29, 0xffff0000, v179
	v_sub_f32_e32 v22, v22, v201
	v_sub_f32_e32 v23, v23, v201
	v_sub_f32_e32 v24, v24, v201
	v_sub_f32_e32 v25, v25, v201
	v_sub_f32_e32 v26, v26, v201
	v_sub_f32_e32 v27, v27, v201
	v_sub_f32_e32 v28, v28, v201
	v_sub_f32_e32 v29, v29, v201
	v_mul_f32_e32 v22, v22, v200
	v_mul_f32_e32 v23, v23, v200
	v_mul_f32_e32 v24, v24, v200
	v_mul_f32_e32 v25, v25, v200
	v_mul_f32_e32 v26, v26, v200
	v_mul_f32_e32 v27, v27, v200
	v_mul_f32_e32 v28, v28, v200
	v_mul_f32_e32 v29, v29, v200
	v_fma_f32 v22, v144, v22, v152
	v_fma_f32 v23, v145, v23, v153
	v_fma_f32 v24, v146, v24, v154
	v_fma_f32 v25, v147, v25, v155
	v_fma_f32 v26, v148, v26, v156
	v_fma_f32 v27, v149, v27, v157
	v_fma_f32 v28, v150, v28, v158
	v_fma_f32 v29, v151, v29, v159
	v_cvt_pk_bf16_f32 v18, v22, v23
	v_cvt_pk_bf16_f32 v19, v24, v25
	v_cvt_pk_bf16_f32 v20, v26, v27
	v_cvt_pk_bf16_f32 v21, v28, v29
	ds_write_b128 v109, v[18:21]
	s_waitcnt vmcnt(14)
	v_pk_mul_f32 v[202:203], v[202:203], s[10:11] op_sel_hi:[1,0]
	s_nop 0
	v_fma_f32 v202, -v203, v203, v202
	v_add_f32_e32 v202, 0x358637bd, v202
	v_rsq_f32_e32 v202, v202
	v_lshlrev_b32_e32 v22, 16, v180
	v_and_b32_e32 v23, 0xffff0000, v180
	v_lshlrev_b32_e32 v24, 16, v181
	v_and_b32_e32 v25, 0xffff0000, v181
	v_lshlrev_b32_e32 v26, 16, v182
	v_and_b32_e32 v27, 0xffff0000, v182
	v_lshlrev_b32_e32 v28, 16, v183
	v_and_b32_e32 v29, 0xffff0000, v183
	v_sub_f32_e32 v22, v22, v203
	v_sub_f32_e32 v23, v23, v203
	v_sub_f32_e32 v24, v24, v203
	v_sub_f32_e32 v25, v25, v203
	v_sub_f32_e32 v26, v26, v203
	v_sub_f32_e32 v27, v27, v203
	v_sub_f32_e32 v28, v28, v203
	v_sub_f32_e32 v29, v29, v203
	v_mul_f32_e32 v22, v22, v202
	v_mul_f32_e32 v23, v23, v202
	v_mul_f32_e32 v24, v24, v202
	v_mul_f32_e32 v25, v25, v202
	v_mul_f32_e32 v26, v26, v202
	v_mul_f32_e32 v27, v27, v202
	v_mul_f32_e32 v28, v28, v202
	v_mul_f32_e32 v29, v29, v202
	v_fma_f32 v22, v144, v22, v152
	v_fma_f32 v23, v145, v23, v153
	v_fma_f32 v24, v146, v24, v154
	v_fma_f32 v25, v147, v25, v155
	v_fma_f32 v26, v148, v26, v156
	v_fma_f32 v27, v149, v27, v157
	v_fma_f32 v28, v150, v28, v158
	v_fma_f32 v29, v151, v29, v159
	v_cvt_pk_bf16_f32 v30, v22, v23
	v_cvt_pk_bf16_f32 v31, v24, v25
	v_cvt_pk_bf16_f32 v32, v26, v27
	v_cvt_pk_bf16_f32 v33, v28, v29
	ds_write_b128 v110, v[30:33]
	s_waitcnt vmcnt(11)
	v_pk_mul_f32 v[204:205], v[204:205], s[10:11] op_sel_hi:[1,0]
	s_nop 0
	v_fma_f32 v204, -v205, v205, v204
	v_add_f32_e32 v204, 0x358637bd, v204
	v_rsq_f32_e32 v204, v204
	v_lshlrev_b32_e32 v22, 16, v184
	v_and_b32_e32 v23, 0xffff0000, v184
	v_lshlrev_b32_e32 v24, 16, v185
	v_and_b32_e32 v25, 0xffff0000, v185
	v_lshlrev_b32_e32 v26, 16, v186
	v_and_b32_e32 v27, 0xffff0000, v186
	v_lshlrev_b32_e32 v28, 16, v187
	v_and_b32_e32 v29, 0xffff0000, v187
	v_sub_f32_e32 v22, v22, v205
	v_sub_f32_e32 v23, v23, v205
	v_sub_f32_e32 v24, v24, v205
	v_sub_f32_e32 v25, v25, v205
	v_sub_f32_e32 v26, v26, v205
	v_sub_f32_e32 v27, v27, v205
	v_sub_f32_e32 v28, v28, v205
	v_sub_f32_e32 v29, v29, v205
	v_mul_f32_e32 v22, v22, v204
	v_mul_f32_e32 v23, v23, v204
	v_mul_f32_e32 v24, v24, v204
	v_mul_f32_e32 v25, v25, v204
	v_mul_f32_e32 v26, v26, v204
	v_mul_f32_e32 v27, v27, v204
	v_mul_f32_e32 v28, v28, v204
	v_mul_f32_e32 v29, v29, v204
	v_fma_f32 v22, v144, v22, v152
	v_fma_f32 v23, v145, v23, v153
	v_fma_f32 v24, v146, v24, v154
	v_fma_f32 v25, v147, v25, v155
	v_fma_f32 v26, v148, v26, v156
	v_fma_f32 v27, v149, v27, v157
	v_fma_f32 v28, v150, v28, v158
	v_fma_f32 v29, v151, v29, v159
	v_cvt_pk_bf16_f32 v18, v22, v23
	v_cvt_pk_bf16_f32 v19, v24, v25
	v_cvt_pk_bf16_f32 v20, v26, v27
	v_cvt_pk_bf16_f32 v21, v28, v29
	ds_write_b128 v111, v[18:21]
	s_waitcnt vmcnt(8)
	v_pk_mul_f32 v[206:207], v[206:207], s[10:11] op_sel_hi:[1,0]
	s_nop 0
	v_fma_f32 v206, -v207, v207, v206
	v_add_f32_e32 v206, 0x358637bd, v206
	v_rsq_f32_e32 v206, v206
	v_lshlrev_b32_e32 v22, 16, v188
	v_and_b32_e32 v23, 0xffff0000, v188
	v_lshlrev_b32_e32 v24, 16, v189
	v_and_b32_e32 v25, 0xffff0000, v189
	v_lshlrev_b32_e32 v26, 16, v190
	v_and_b32_e32 v27, 0xffff0000, v190
	v_lshlrev_b32_e32 v28, 16, v191
	v_and_b32_e32 v29, 0xffff0000, v191
	v_sub_f32_e32 v22, v22, v207
	v_sub_f32_e32 v23, v23, v207
	v_sub_f32_e32 v24, v24, v207
	v_sub_f32_e32 v25, v25, v207
	v_sub_f32_e32 v26, v26, v207
	v_sub_f32_e32 v27, v27, v207
	v_sub_f32_e32 v28, v28, v207
	v_sub_f32_e32 v29, v29, v207
	v_mul_f32_e32 v22, v22, v206
	v_mul_f32_e32 v23, v23, v206
	v_mul_f32_e32 v24, v24, v206
	v_mul_f32_e32 v25, v25, v206
	v_mul_f32_e32 v26, v26, v206
	v_mul_f32_e32 v27, v27, v206
	v_mul_f32_e32 v28, v28, v206
	v_mul_f32_e32 v29, v29, v206
	v_fma_f32 v22, v144, v22, v152
	v_fma_f32 v23, v145, v23, v153
	v_fma_f32 v24, v146, v24, v154
	v_fma_f32 v25, v147, v25, v155
	v_fma_f32 v26, v148, v26, v156
	v_fma_f32 v27, v149, v27, v157
	v_fma_f32 v28, v150, v28, v158
	v_fma_f32 v29, v151, v29, v159
	v_cvt_pk_bf16_f32 v30, v22, v23
	v_cvt_pk_bf16_f32 v31, v24, v25
	v_cvt_pk_bf16_f32 v32, v26, v27
	v_cvt_pk_bf16_f32 v33, v28, v29
	ds_write_b128 v112, v[30:33]
	s_waitcnt lgkmcnt(0)
	s_barrier
	v_add_u32_e32 v244, s6, v84
	v_ashrrev_i32_e32 v245, 31, v244
	v_lshlrev_b64 v[244:245], 11, v[244:245]
	v_lshl_add_u64 v[244:245], s[46:47], 0, v[244:245]
	v_lshl_add_u64 v[244:245], v[244:245], 0, s[8:9]
	v_lshl_add_u64 v[244:245], v[244:245], 0, v[76:77]
	v_bfe_u32 v228, v230, 4, 1
	v_mul_u32_u24_e32 v228, 24, v228
	v_mov_b32_e32 v229, 0
	v_lshl_add_u64 v[228:229], v[244:245], 0, v[228:229]
	global_load_dwordx4 v[144:147], v[228:229], off
	global_load_dwordx4 v[148:151], v[228:229], off offset:64
	global_load_dwordx4 v[152:155], v[228:229], off offset:128
	global_load_dwordx4 v[156:159], v[228:229], off offset:192
	global_load_dwordx4 v[160:163], v[228:229], off offset:256
	global_load_dwordx4 v[164:167], v[228:229], off offset:320
	global_load_dwordx4 v[168:171], v[228:229], off offset:384
	global_load_dwordx4 v[172:175], v[228:229], off offset:448
	v_add_u32_e32 v246, s0, v84
	v_ashrrev_i32_e32 v247, 31, v246
	v_lshl_add_u64 v[246:247], v[246:247], 2, s[42:43]
	global_load_dword v113, v[246:247], off
	s_waitcnt vmcnt(9)
	v_cvt_pk_bf16_f32 v12, v208, v209
	v_cvt_pk_bf16_f32 v13, v210, v211
	v_cvt_pk_bf16_f32 v14, v212, v213
	v_cvt_pk_bf16_f32 v15, v214, v215
	v_cvt_pk_bf16_f32 v8, v216, v217
	v_cvt_pk_bf16_f32 v9, v218, v219
	v_cvt_pk_bf16_f32 v10, v220, v221
	v_cvt_pk_bf16_f32 v11, v222, v223
	v_cvt_pk_bf16_f32 v4, v224, v225
	v_cvt_pk_bf16_f32 v5, v226, v227
	v_cvt_pk_bf16_f32 v6, v232, v233
	v_cvt_pk_bf16_f32 v7, v234, v235
	v_cvt_pk_bf16_f32 v0, v236, v237
	v_cvt_pk_bf16_f32 v1, v238, v239
	v_cvt_pk_bf16_f32 v2, v240, v241
	v_cvt_pk_bf16_f32 v3, v242, v243
	ds_read_b64_tr_b16 v[16:17], v104
	ds_read_b64_tr_b16 v[18:19], v104 offset:8704
	ds_read_b64_tr_b16 v[22:23], v104 offset:8736
	ds_read_b64_tr_b16 v[20:21], v104 offset:32
	ds_read_b64_tr_b16 v[24:25], v104 offset:64
	ds_read_b64_tr_b16 v[28:29], v104 offset:96
	ds_read_b64_tr_b16 v[26:27], v104 offset:8768
	ds_read_b64_tr_b16 v[30:31], v104 offset:8800
	ds_read_b64_tr_b16 v[32:33], v104 offset:128
	ds_read_b64_tr_b16 v[34:35], v104 offset:8832
	ds_read_b64_tr_b16 v[38:39], v104 offset:8864
	ds_read_b64_tr_b16 v[36:37], v104 offset:160
	ds_read_b64_tr_b16 v[40:41], v104 offset:192
	ds_read_b64_tr_b16 v[44:45], v104 offset:224
	ds_read_b64_tr_b16 v[42:43], v104 offset:8896
	ds_read_b64_tr_b16 v[46:47], v104 offset:8928
	ds_read_b64_tr_b16 v[48:49], v104 offset:256
	ds_read_b64_tr_b16 v[50:51], v104 offset:8960
	ds_read_b64_tr_b16 v[54:55], v104 offset:8992
	ds_read_b64_tr_b16 v[52:53], v104 offset:288
	ds_read_b64_tr_b16 v[56:57], v104 offset:320
	ds_read_b64_tr_b16 v[60:61], v104 offset:352
	ds_read_b64_tr_b16 v[58:59], v104 offset:9024
	ds_read_b64_tr_b16 v[62:63], v104 offset:9056
	ds_read_b64_tr_b16 v[64:65], v104 offset:384
	ds_read_b64_tr_b16 v[66:67], v104 offset:9088
	ds_read_b64_tr_b16 v[70:71], v104 offset:9120
	ds_read_b64_tr_b16 v[68:69], v104 offset:416
	ds_read_b64_tr_b16 v[72:73], v104 offset:448
	ds_read_b64_tr_b16 v[90:91], v104 offset:480
	ds_read_b64_tr_b16 v[74:75], v104 offset:9152
	ds_read_b64_tr_b16 v[92:93], v104 offset:9184
	ds_read_b64_tr_b16 v[114:115], v104 offset:17408
	ds_read_b64_tr_b16 v[116:117], v104 offset:26112
	s_waitcnt lgkmcnt(14)
	v_mfma_f32_16x16x32_bf16 v[16:19], v[16:19], v[12:15], 0
	ds_read_b64_tr_b16 v[120:121], v104 offset:26144
	ds_read_b64_tr_b16 v[118:119], v104 offset:17440
	ds_read_b64_tr_b16 v[122:123], v104 offset:17472
	v_mfma_f32_16x16x32_bf16 v[20:23], v[20:23], v[12:15], 0
	v_mfma_f32_16x16x32_bf16 v[24:27], v[24:27], v[12:15], 0
	v_mfma_f32_16x16x32_bf16 v[28:31], v[28:31], v[12:15], 0
	v_mfma_f32_16x16x32_bf16 v[32:35], v[32:35], v[12:15], 0
	v_mfma_f32_16x16x32_bf16 v[36:39], v[36:39], v[12:15], 0
	v_mfma_f32_16x16x32_bf16 v[40:43], v[40:43], v[12:15], 0
	v_mfma_f32_16x16x32_bf16 v[44:47], v[44:47], v[12:15], 0
	v_mfma_f32_16x16x32_bf16 v[48:51], v[48:51], v[12:15], 0
	v_mfma_f32_16x16x32_bf16 v[52:55], v[52:55], v[12:15], 0
	s_waitcnt lgkmcnt(14)
	v_mfma_f32_16x16x32_bf16 v[56:59], v[56:59], v[12:15], 0
	s_waitcnt lgkmcnt(13)
	v_mfma_f32_16x16x32_bf16 v[60:63], v[60:63], v[12:15], 0
	s_waitcnt lgkmcnt(11)
	v_mfma_f32_16x16x32_bf16 v[64:67], v[64:67], v[12:15], 0
	s_waitcnt lgkmcnt(9)
	v_mfma_f32_16x16x32_bf16 v[68:71], v[68:71], v[12:15], 0
	s_waitcnt lgkmcnt(6)
	v_mfma_f32_16x16x32_bf16 v[72:75], v[72:75], v[12:15], 0
	s_waitcnt lgkmcnt(5)
	v_mfma_f32_16x16x32_bf16 v[12:15], v[90:93], v[12:15], 0
	ds_read_b64_tr_b16 v[90:91], v104 offset:17504
	ds_read_b64_tr_b16 v[124:125], v104 offset:26176
	ds_read_b64_tr_b16 v[92:93], v104 offset:26208
	s_waitcnt lgkmcnt(6)
	v_mfma_f32_16x16x32_bf16 v[16:19], v[114:117], v[8:11], v[16:19]
	ds_read_b64_tr_b16 v[114:115], v104 offset:17536
	ds_read_b64_tr_b16 v[116:117], v104 offset:26240
	s_waitcnt lgkmcnt(6)
	v_mfma_f32_16x16x32_bf16 v[20:23], v[118:121], v[8:11], v[20:23]
	s_waitcnt lgkmcnt(3)
	v_mfma_f32_16x16x32_bf16 v[24:27], v[122:125], v[8:11], v[24:27]
	ds_read_b64_tr_b16 v[120:121], v104 offset:26272
	ds_read_b64_tr_b16 v[118:119], v104 offset:17568
	ds_read_b64_tr_b16 v[122:123], v104 offset:17600
	s_waitcnt lgkmcnt(5)
	v_mfma_f32_16x16x32_bf16 v[28:31], v[90:93], v[8:11], v[28:31]
	ds_read_b64_tr_b16 v[90:91], v104 offset:17632
	ds_read_b64_tr_b16 v[124:125], v104 offset:26304
	ds_read_b64_tr_b16 v[92:93], v104 offset:26336
	s_waitcnt lgkmcnt(6)
	v_mfma_f32_16x16x32_bf16 v[32:35], v[114:117], v[8:11], v[32:35]
	ds_read_b64_tr_b16 v[114:115], v104 offset:17664
	ds_read_b64_tr_b16 v[116:117], v104 offset:26368
	s_waitcnt lgkmcnt(6)
	v_mfma_f32_16x16x32_bf16 v[36:39], v[118:121], v[8:11], v[36:39]
	s_waitcnt lgkmcnt(3)
	v_mfma_f32_16x16x32_bf16 v[40:43], v[122:125], v[8:11], v[40:43]
	ds_read_b64_tr_b16 v[120:121], v104 offset:26400
	ds_read_b64_tr_b16 v[118:119], v104 offset:17696
	ds_read_b64_tr_b16 v[122:123], v104 offset:17728
	s_waitcnt lgkmcnt(5)
	v_mfma_f32_16x16x32_bf16 v[44:47], v[90:93], v[8:11], v[44:47]
	ds_read_b64_tr_b16 v[90:91], v104 offset:17760
	ds_read_b64_tr_b16 v[124:125], v104 offset:26432
	ds_read_b64_tr_b16 v[92:93], v104 offset:26464
	s_waitcnt lgkmcnt(6)
	v_mfma_f32_16x16x32_bf16 v[48:51], v[114:117], v[8:11], v[48:51]
	ds_read_b64_tr_b16 v[114:115], v104 offset:17792
	ds_read_b64_tr_b16 v[116:117], v104 offset:26496
	s_waitcnt lgkmcnt(6)
	v_mfma_f32_16x16x32_bf16 v[52:55], v[118:121], v[8:11], v[52:55]
	s_waitcnt lgkmcnt(3)
	v_mfma_f32_16x16x32_bf16 v[56:59], v[122:125], v[8:11], v[56:59]
	ds_read_b64_tr_b16 v[120:121], v104 offset:26528
	ds_read_b64_tr_b16 v[118:119], v104 offset:17824
	ds_read_b64_tr_b16 v[122:123], v104 offset:17856
	s_waitcnt lgkmcnt(5)
	v_mfma_f32_16x16x32_bf16 v[60:63], v[90:93], v[8:11], v[60:63]
	ds_read_b64_tr_b16 v[90:91], v104 offset:17888
	ds_read_b64_tr_b16 v[124:125], v104 offset:26560
	ds_read_b64_tr_b16 v[92:93], v104 offset:26592
	s_waitcnt lgkmcnt(6)
	v_mfma_f32_16x16x32_bf16 v[64:67], v[114:117], v[8:11], v[64:67]
	ds_read_b64_tr_b16 v[114:115], v104 offset:34816
	ds_read_b64_tr_b16 v[116:117], v104 offset:43520
	s_waitcnt lgkmcnt(6)
	v_mfma_f32_16x16x32_bf16 v[68:71], v[118:121], v[8:11], v[68:71]
	s_waitcnt lgkmcnt(3)
	v_mfma_f32_16x16x32_bf16 v[72:75], v[122:125], v[8:11], v[72:75]
	ds_read_b64_tr_b16 v[120:121], v104 offset:43552
	ds_read_b64_tr_b16 v[118:119], v104 offset:34848
	ds_read_b64_tr_b16 v[122:123], v104 offset:34880
	s_waitcnt lgkmcnt(5)
	v_mfma_f32_16x16x32_bf16 v[8:11], v[90:93], v[8:11], v[12:15]
	s_nop 2
	ds_read_b64_tr_b16 v[12:13], v104 offset:34912
	ds_read_b64_tr_b16 v[124:125], v104 offset:43584
	ds_read_b64_tr_b16 v[14:15], v104 offset:43616
	s_waitcnt lgkmcnt(6)
	v_mfma_f32_16x16x32_bf16 v[16:19], v[114:117], v[4:7], v[16:19]
	s_waitcnt lgkmcnt(4)
	v_mfma_f32_16x16x32_bf16 v[90:93], v[118:121], v[4:7], v[20:23]
	s_nop 2
	ds_read_b64_tr_b16 v[20:21], v104 offset:34944
	ds_read_b64_tr_b16 v[22:23], v104 offset:43648
	ds_read_b64_tr_b16 v[116:117], v104 offset:43680
	ds_read_b64_tr_b16 v[114:115], v104 offset:34976
	ds_read_b64_tr_b16 v[118:119], v104 offset:35008
	s_waitcnt lgkmcnt(5)
	v_mfma_f32_16x16x32_bf16 v[28:31], v[12:15], v[4:7], v[28:31]
	ds_read_b64_tr_b16 v[12:13], v104 offset:35040
	ds_read_b64_tr_b16 v[120:121], v104 offset:43712
	ds_read_b64_tr_b16 v[14:15], v104 offset:43744
	s_waitcnt lgkmcnt(6)
	v_mfma_f32_16x16x32_bf16 v[32:35], v[20:23], v[4:7], v[32:35]
	ds_read_b64_tr_b16 v[20:21], v104 offset:35072
	ds_read_b64_tr_b16 v[22:23], v104 offset:43776
	s_waitcnt lgkmcnt(6)
	v_mfma_f32_16x16x32_bf16 v[36:39], v[114:117], v[4:7], v[36:39]
	s_waitcnt lgkmcnt(3)
	v_mfma_f32_16x16x32_bf16 v[40:43], v[118:121], v[4:7], v[40:43]
	ds_read_b64_tr_b16 v[116:117], v104 offset:43808
	ds_read_b64_tr_b16 v[114:115], v104 offset:35104
	ds_read_b64_tr_b16 v[118:119], v104 offset:35136
	s_waitcnt lgkmcnt(5)
	v_mfma_f32_16x16x32_bf16 v[44:47], v[12:15], v[4:7], v[44:47]
	ds_read_b64_tr_b16 v[12:13], v104 offset:35168
	ds_read_b64_tr_b16 v[120:121], v104 offset:43840
	ds_read_b64_tr_b16 v[14:15], v104 offset:43872
	s_waitcnt lgkmcnt(6)
	v_mfma_f32_16x16x32_bf16 v[48:51], v[20:23], v[4:7], v[48:51]
	ds_read_b64_tr_b16 v[20:21], v104 offset:35200
	ds_read_b64_tr_b16 v[22:23], v104 offset:43904
	s_waitcnt lgkmcnt(6)
	v_mfma_f32_16x16x32_bf16 v[114:117], v[114:117], v[4:7], v[52:55]
	s_waitcnt lgkmcnt(3)
	v_mfma_f32_16x16x32_bf16 v[118:121], v[118:121], v[4:7], v[56:59]
	s_nop 0
	ds_read_b64_tr_b16 v[54:55], v104 offset:43936
	ds_read_b64_tr_b16 v[52:53], v104 offset:35232
	ds_read_b64_tr_b16 v[56:57], v104 offset:35264
	v_mfma_f32_16x16x32_bf16 v[24:27], v[122:125], v[4:7], v[24:27]
	s_waitcnt lgkmcnt(5)
	v_mfma_f32_16x16x32_bf16 v[122:125], v[12:15], v[4:7], v[60:63]
	ds_read_b64_tr_b16 v[12:13], v104 offset:35296
	ds_read_b64_tr_b16 v[58:59], v104 offset:43968
	ds_read_b64_tr_b16 v[14:15], v104 offset:44000
	ds_read_b64_tr_b16 v[60:61], v104 offset:52224
	ds_read_b64_tr_b16 v[62:63], v104 offset:60928
	s_waitcnt lgkmcnt(8)
	v_mfma_f32_16x16x32_bf16 v[126:129], v[20:23], v[4:7], v[64:67]
	s_waitcnt lgkmcnt(6)
	v_mfma_f32_16x16x32_bf16 v[130:133], v[52:55], v[4:7], v[68:71]
	ds_read_b64_tr_b16 v[54:55], v104 offset:60960
	ds_read_b64_tr_b16 v[52:53], v104 offset:52256
	ds_read_b64_tr_b16 v[64:65], v104 offset:52288
	s_waitcnt lgkmcnt(6)
	v_mfma_f32_16x16x32_bf16 v[20:23], v[56:59], v[4:7], v[72:75]
	ds_read_b64_tr_b16 v[56:57], v104 offset:52320
	ds_read_b64_tr_b16 v[66:67], v104 offset:60992
	ds_read_b64_tr_b16 v[58:59], v104 offset:61024
	s_waitcnt lgkmcnt(6)
	v_mfma_f32_16x16x32_bf16 v[134:137], v[60:63], v[0:3], v[16:19]
	s_nop 2
	ds_read_b64_tr_b16 v[16:17], v104 offset:52352
	ds_read_b64_tr_b16 v[18:19], v104 offset:61056
	v_add_u32_e32 v60, s6, v84
	v_ashrrev_i32_e32 v61, 31, v60
	s_waitcnt lgkmcnt(6)
	v_mfma_f32_16x16x32_bf16 v[138:141], v[52:55], v[0:3], v[90:93]
	s_waitcnt lgkmcnt(3)
	v_mfma_f32_16x16x32_bf16 v[72:75], v[64:67], v[0:3], v[24:27]
	s_nop 2
	ds_read_b64_tr_b16 v[26:27], v104 offset:61088
	ds_read_b64_tr_b16 v[24:25], v104 offset:52384
	ds_read_b64_tr_b16 v[52:53], v104 offset:52416
	v_lshlrev_b64 v[92:93], 11, v[60:61]
	v_add_u32_e32 v90, s0, v84
	s_waitcnt lgkmcnt(5)
	v_mfma_f32_16x16x32_bf16 v[68:71], v[56:59], v[0:3], v[28:31]
	s_nop 2
	ds_read_b64_tr_b16 v[28:29], v104 offset:52448
	ds_read_b64_tr_b16 v[54:55], v104 offset:61120
	ds_read_b64_tr_b16 v[30:31], v104 offset:61152
	v_ashrrev_i32_e32 v91, 31, v90
	v_lshl_add_u64 v[142:143], v[90:91], 2, s[42:43]
	s_waitcnt lgkmcnt(6)
	v_mfma_f32_16x16x32_bf16 v[64:67], v[16:19], v[0:3], v[32:35]
	ds_read_b64_tr_b16 v[16:17], v104 offset:52480
	ds_read_b64_tr_b16 v[18:19], v104 offset:61184
	s_waitcnt lgkmcnt(6)
	v_mfma_f32_16x16x32_bf16 v[60:63], v[24:27], v[0:3], v[36:39]
	ds_read_b64_tr_b16 v[26:27], v104 offset:61216
	ds_read_b64_tr_b16 v[24:25], v104 offset:52512
	ds_read_b64_tr_b16 v[32:33], v104 offset:52544
	s_waitcnt lgkmcnt(6)
	v_mfma_f32_16x16x32_bf16 v[56:59], v[52:55], v[0:3], v[40:43]
	s_waitcnt lgkmcnt(5)
	v_mfma_f32_16x16x32_bf16 v[52:55], v[28:31], v[0:3], v[44:47]
	ds_read_b64_tr_b16 v[28:29], v104 offset:52576
	ds_read_b64_tr_b16 v[34:35], v104 offset:61248
	ds_read_b64_tr_b16 v[30:31], v104 offset:61280
	s_waitcnt lgkmcnt(6)
	v_mfma_f32_16x16x32_bf16 v[48:51], v[16:19], v[0:3], v[48:51]
	v_lshl_add_u64 v[16:17], s[46:47], 0, v[92:93]
	v_lshl_add_u64 v[16:17], v[16:17], 0, s[8:9]
	v_lshl_add_u64 v[90:91], v[16:17], 0, v[76:77]
	s_waitcnt lgkmcnt(4)
	v_mfma_f32_16x16x32_bf16 v[44:47], v[24:27], v[0:3], v[114:117]
	ds_read_b64_tr_b16 v[94:95], v104 offset:61312
	ds_read_b64_tr_b16 v[92:93], v104 offset:52608
	s_nop 0
	ds_read_b64_tr_b16 v[114:115], v104 offset:52640
	ds_read_b64_tr_b16 v[24:25], v104 offset:52672
	ds_read_b64_tr_b16 v[16:17], v104 offset:52704
	s_waitcnt lgkmcnt(6)
	v_mfma_f32_16x16x32_bf16 v[40:43], v[32:35], v[0:3], v[118:121]
	s_nop 2
	s_waitcnt vmcnt(0)
	v_permlane16_swap_b32_e32 v144, v146
	v_permlane16_swap_b32_e32 v145, v147
	v_permlane16_swap_b32_e32 v148, v150
	v_permlane16_swap_b32_e32 v149, v151
	v_permlane16_swap_b32_e32 v152, v154
	v_permlane16_swap_b32_e32 v153, v155
	v_permlane16_swap_b32_e32 v156, v158
	v_permlane16_swap_b32_e32 v157, v159
	v_permlane16_swap_b32_e32 v160, v162
	v_permlane16_swap_b32_e32 v161, v163
	v_permlane16_swap_b32_e32 v164, v166
	v_permlane16_swap_b32_e32 v165, v167
	v_permlane16_swap_b32_e32 v168, v170
	v_permlane16_swap_b32_e32 v169, v171
	v_permlane16_swap_b32_e32 v172, v174
	v_permlane16_swap_b32_e32 v173, v175
	s_nop 1
	v_mov_b64_e32 v[118:119], v[144:145]
	ds_read_b64_tr_b16 v[116:117], v104 offset:61344
	ds_read_b64_tr_b16 v[26:27], v104 offset:61376
	ds_read_b64_tr_b16 v[18:19], v104 offset:61408
	s_waitcnt lgkmcnt(6)
	v_mfma_f32_16x16x32_bf16 v[32:35], v[92:95], v[0:3], v[126:129]
	v_lshlrev_b32_e32 v92, 16, v118
	v_and_b32_e32 v93, 0xffff0000, v118
	v_lshlrev_b32_e32 v94, 16, v119
	v_and_b32_e32 v95, 0xffff0000, v119
	v_mfma_f32_16x16x32_bf16 v[36:39], v[28:31], v[0:3], v[122:125]
	v_and_b32_e32 v127, 0x7fffffff, v95
	v_and_b32_e32 v126, 0x7fffffff, v94
	v_pk_fma_f32 v[126:127], v[126:127], s[12:13], 1.0 op_sel_hi:[1,0,0]
	v_and_b32_e32 v123, 0x7fffffff, v93
	v_and_b32_e32 v122, 0x7fffffff, v92
	v_pk_fma_f32 v[122:123], v[122:123], s[12:13], 1.0 op_sel_hi:[1,0,0]
	v_rcp_f32_e32 v126, v126
	v_rcp_f32_e32 v122, v122
	v_rcp_f32_e32 v123, v123
	v_rcp_f32_e32 v127, v127
	v_pk_mul_f32 v[124:125], v[92:93], v[92:93]
	v_pk_mul_f32 v[128:129], v[94:95], v[94:95]
	s_waitcnt lgkmcnt(2)
	v_mfma_f32_16x16x32_bf16 v[28:31], v[114:117], v[0:3], v[130:133]
	v_mul_f32_e64 v124, v124, s62
	v_mul_f32_e64 v125, v125, s62
	v_pk_mul_f32 v[128:129], v[128:129], s[62:63] op_sel_hi:[1,0]
	v_exp_f32_e32 v124, v124
	v_pk_fma_f32 v[130:131], v[122:123], s[36:37], v[88:89] op_sel_hi:[1,0,0]
	v_pk_fma_f32 v[132:133], v[126:127], s[36:37], v[88:89] op_sel_hi:[1,0,0]
	v_exp_f32_e32 v125, v125
	v_exp_f32_e32 v128, v128
	v_exp_f32_e32 v129, v129
	v_pk_fma_f32 v[130:131], v[122:123], v[130:131], s[38:39] op_sel_hi:[1,1,0]
	v_pk_fma_f32 v[132:133], v[126:127], v[132:133], s[38:39] op_sel_hi:[1,1,0]
	v_pk_fma_f32 v[130:131], v[122:123], v[130:131], s[40:41] op_sel_hi:[1,1,0]
	v_pk_fma_f32 v[132:133], v[126:127], v[132:133], s[40:41] op_sel_hi:[1,1,0]
	v_pk_fma_f32 v[130:131], v[122:123], v[130:131], s[60:61] op_sel_hi:[1,1,0]
	v_pk_fma_f32 v[132:133], v[126:127], v[132:133], s[60:61] op_sel_hi:[1,1,0]
	v_pk_mul_f32 v[122:123], v[122:123], v[130:131]
	v_pk_mul_f32 v[126:127], v[126:127], v[132:133]
	v_pk_mul_f32 v[122:123], v[124:125], v[122:123]
	v_pk_mul_f32 v[124:125], v[128:129], v[126:127]
	v_pk_mul_f32 v[126:127], v[92:93], v[122:123]
	v_pk_fma_f32 v[122:123], v[92:93], v[122:123], v[92:93] neg_lo:[1,0,0] neg_hi:[1,0,0]
	v_cmp_gt_f32_e32 vcc, 0, v93
	v_pk_mul_f32 v[128:129], v[94:95], v[124:125]
	v_pk_fma_f32 v[124:125], v[94:95], v[124:125], v[94:95] neg_lo:[1,0,0] neg_hi:[1,0,0]
	v_cmp_gt_f32_e64 s[0:1], 0, v94
	v_cmp_gt_f32_e64 s[4:5], 0, v95
	v_cmp_gt_f32_e64 s[6:7], 0, v92
	v_add_f32_e32 v114, v134, v113
	v_add_f32_e32 v115, v135, v113
	v_add_f32_e32 v116, v136, v113
	v_add_f32_e32 v117, v137, v113
	v_cndmask_b32_e64 v92, v122, v126, s[6:7]
	v_cndmask_b32_e32 v93, v123, v127, vcc
	v_cndmask_b32_e64 v94, v124, v128, s[0:1]
	v_cndmask_b32_e64 v95, v125, v129, s[4:5]
	v_mul_f32_e32 v92, v114, v92
	v_mul_f32_e32 v93, v115, v93
	v_mul_f32_e32 v94, v116, v94
	v_mul_f32_e32 v95, v117, v95
	v_cvt_pk_bf16_f32 v92, v92, v93
	v_cvt_pk_bf16_f32 v93, v94, v95
	v_mov_b64_e32 v[94:95], v[146:147]
	v_add_f32_e32 v118, v138, v113
	v_mov_b64_e32 v[250:251], v[92:93]
	v_add_f32_e32 v119, v139, v113
	v_add_f32_e32 v120, v140, v113
	v_add_f32_e32 v121, v141, v113
	v_add_f32_e32 v72, v72, v113
	v_add_f32_e32 v73, v73, v113
	v_add_f32_e32 v74, v74, v113
	v_add_f32_e32 v75, v75, v113
	v_add_f32_e32 v68, v68, v113
	v_add_f32_e32 v69, v69, v113
	v_add_f32_e32 v70, v70, v113
	v_add_f32_e32 v71, v71, v113
	v_add_f32_e32 v64, v64, v113
	v_add_f32_e32 v65, v65, v113
	v_add_f32_e32 v66, v66, v113
	v_add_f32_e32 v67, v67, v113
	v_add_f32_e32 v60, v60, v113
	v_add_f32_e32 v61, v61, v113
	v_add_f32_e32 v62, v62, v113
	v_add_f32_e32 v63, v63, v113
	v_add_f32_e32 v56, v56, v113
	v_add_f32_e32 v57, v57, v113
	v_add_f32_e32 v58, v58, v113
	v_add_f32_e32 v59, v59, v113
	v_add_f32_e32 v52, v52, v113
	v_add_f32_e32 v53, v53, v113
	v_add_f32_e32 v54, v54, v113
	v_add_f32_e32 v55, v55, v113
	v_add_f32_e32 v48, v48, v113
	v_add_f32_e32 v49, v49, v113
	v_add_f32_e32 v50, v50, v113
	v_add_f32_e32 v51, v51, v113
	v_add_f32_e32 v44, v44, v113
	v_add_f32_e32 v45, v45, v113
	v_add_f32_e32 v46, v46, v113
	v_add_f32_e32 v47, v47, v113
	v_add_f32_e32 v40, v40, v113
	v_add_f32_e32 v41, v41, v113
	v_add_f32_e32 v42, v42, v113
	v_add_f32_e32 v43, v43, v113
	v_add_f32_e32 v36, v36, v113
	v_add_f32_e32 v37, v37, v113
	v_add_f32_e32 v38, v38, v113
	v_add_f32_e32 v39, v39, v113
	v_add_f32_e32 v32, v32, v113
	v_add_f32_e32 v33, v33, v113
	v_add_f32_e32 v34, v34, v113
	v_add_f32_e32 v35, v35, v113
	v_add_f32_e32 v28, v28, v113
	v_add_f32_e32 v29, v29, v113
	v_add_f32_e32 v30, v30, v113
	v_add_f32_e32 v31, v31, v113
	s_waitcnt lgkmcnt(1)
	v_mfma_f32_16x16x32_bf16 v[20:23], v[24:27], v[0:3], v[20:23]
	v_lshlrev_b32_e32 v92, 16, v94
	v_and_b32_e32 v93, 0xffff0000, v94
	v_lshlrev_b32_e32 v94, 16, v95
	v_and_b32_e32 v95, 0xffff0000, v95
	v_and_b32_e32 v115, 0x7fffffff, v93
	v_and_b32_e32 v114, 0x7fffffff, v92
	v_and_b32_e32 v123, 0x7fffffff, v95
	v_and_b32_e32 v122, 0x7fffffff, v94
	v_pk_fma_f32 v[114:115], v[114:115], s[12:13], 1.0 op_sel_hi:[1,0,0]
	v_pk_fma_f32 v[122:123], v[122:123], s[12:13], 1.0 op_sel_hi:[1,0,0]
	v_rcp_f32_e32 v114, v114
	v_rcp_f32_e32 v115, v115
	v_rcp_f32_e32 v122, v122
	v_rcp_f32_e32 v123, v123
	v_pk_mul_f32 v[116:117], v[92:93], v[92:93]
	v_pk_mul_f32 v[124:125], v[94:95], v[94:95]
	v_pk_mul_f32 v[116:117], v[116:117], s[62:63] op_sel_hi:[1,0]
	v_pk_mul_f32 v[124:125], v[124:125], s[62:63] op_sel_hi:[1,0]
	v_pk_fma_f32 v[126:127], v[114:115], s[36:37], v[88:89] op_sel_hi:[1,0,0]
	v_pk_fma_f32 v[128:129], v[122:123], s[36:37], v[88:89] op_sel_hi:[1,0,0]
	v_exp_f32_e32 v116, v116
	v_exp_f32_e32 v117, v117
	v_exp_f32_e32 v124, v124
	v_exp_f32_e32 v125, v125
	v_pk_fma_f32 v[126:127], v[114:115], v[126:127], s[38:39] op_sel_hi:[1,1,0]
	v_pk_fma_f32 v[128:129], v[122:123], v[128:129], s[38:39] op_sel_hi:[1,1,0]
	v_pk_fma_f32 v[126:127], v[114:115], v[126:127], s[40:41] op_sel_hi:[1,1,0]
	v_pk_fma_f32 v[128:129], v[122:123], v[128:129], s[40:41] op_sel_hi:[1,1,0]
	v_pk_fma_f32 v[126:127], v[114:115], v[126:127], s[60:61] op_sel_hi:[1,1,0]
	v_pk_fma_f32 v[128:129], v[122:123], v[128:129], s[60:61] op_sel_hi:[1,1,0]
	v_pk_mul_f32 v[114:115], v[114:115], v[126:127]
	v_pk_mul_f32 v[122:123], v[122:123], v[128:129]
	v_pk_mul_f32 v[114:115], v[116:117], v[114:115]
	v_pk_mul_f32 v[116:117], v[124:125], v[122:123]
	v_pk_mul_f32 v[122:123], v[92:93], v[114:115]
	v_pk_fma_f32 v[114:115], v[92:93], v[114:115], v[92:93] neg_lo:[1,0,0] neg_hi:[1,0,0]
	v_cmp_gt_f32_e32 vcc, 0, v93
	v_pk_mul_f32 v[124:125], v[94:95], v[116:117]
	v_pk_fma_f32 v[116:117], v[94:95], v[116:117], v[94:95] neg_lo:[1,0,0] neg_hi:[1,0,0]
	v_cmp_gt_f32_e64 s[0:1], 0, v94
	v_cmp_gt_f32_e64 s[4:5], 0, v95
	v_cmp_gt_f32_e64 s[6:7], 0, v92
	v_cndmask_b32_e32 v93, v115, v123, vcc
	v_cndmask_b32_e64 v94, v116, v124, s[0:1]
	v_cndmask_b32_e64 v92, v114, v122, s[6:7]
	v_cndmask_b32_e64 v95, v117, v125, s[4:5]
	v_mul_f32_e32 v92, v118, v92
	v_mul_f32_e32 v93, v119, v93
	v_mul_f32_e32 v94, v120, v94
	v_mul_f32_e32 v95, v121, v95
	v_cvt_pk_bf16_f32 v92, v92, v93
	v_cvt_pk_bf16_f32 v93, v94, v95
	v_mov_b64_e32 v[94:95], v[148:149]
	v_mfma_f32_16x16x32_bf16 v[4:7], v[12:15], v[4:7], v[8:11]
	v_mov_b64_e32 v[252:253], v[92:93]
	s_nop 1
	v_permlane16_swap_b32_e32 v250, v252
	v_permlane16_swap_b32_e32 v251, v253
	s_nop 1
	global_store_dwordx4 v[228:229], v[250:253], off
	v_lshlrev_b32_e32 v92, 16, v94
	v_and_b32_e32 v93, 0xffff0000, v94
	v_lshlrev_b32_e32 v94, 16, v95
	v_and_b32_e32 v95, 0xffff0000, v95
	v_and_b32_e32 v115, 0x7fffffff, v93
	v_and_b32_e32 v114, 0x7fffffff, v92
	v_and_b32_e32 v119, 0x7fffffff, v95
	v_and_b32_e32 v118, 0x7fffffff, v94
	v_pk_fma_f32 v[114:115], v[114:115], s[12:13], 1.0 op_sel_hi:[1,0,0]
	v_pk_fma_f32 v[118:119], v[118:119], s[12:13], 1.0 op_sel_hi:[1,0,0]
	v_rcp_f32_e32 v114, v114
	v_rcp_f32_e32 v115, v115
	v_rcp_f32_e32 v118, v118
	v_rcp_f32_e32 v119, v119
	v_pk_mul_f32 v[116:117], v[92:93], v[92:93]
	v_pk_mul_f32 v[120:121], v[94:95], v[94:95]
	v_pk_mul_f32 v[116:117], v[116:117], s[62:63] op_sel_hi:[1,0]
	v_pk_mul_f32 v[120:121], v[120:121], s[62:63] op_sel_hi:[1,0]
	v_pk_fma_f32 v[122:123], v[114:115], s[36:37], v[88:89] op_sel_hi:[1,0,0]
	v_pk_fma_f32 v[124:125], v[118:119], s[36:37], v[88:89] op_sel_hi:[1,0,0]
	v_exp_f32_e32 v116, v116
	v_exp_f32_e32 v117, v117
	v_exp_f32_e32 v120, v120
	v_exp_f32_e32 v121, v121
	v_pk_fma_f32 v[122:123], v[114:115], v[122:123], s[38:39] op_sel_hi:[1,1,0]
	v_pk_fma_f32 v[124:125], v[118:119], v[124:125], s[38:39] op_sel_hi:[1,1,0]
	v_pk_fma_f32 v[122:123], v[114:115], v[122:123], s[40:41] op_sel_hi:[1,1,0]
	v_pk_fma_f32 v[124:125], v[118:119], v[124:125], s[40:41] op_sel_hi:[1,1,0]
	v_pk_fma_f32 v[122:123], v[114:115], v[122:123], s[60:61] op_sel_hi:[1,1,0]
	v_pk_fma_f32 v[124:125], v[118:119], v[124:125], s[60:61] op_sel_hi:[1,1,0]
	v_pk_mul_f32 v[114:115], v[114:115], v[122:123]
	v_pk_mul_f32 v[118:119], v[118:119], v[124:125]
	v_pk_mul_f32 v[114:115], v[116:117], v[114:115]
	v_pk_mul_f32 v[116:117], v[120:121], v[118:119]
	v_pk_mul_f32 v[118:119], v[92:93], v[114:115]
	v_pk_fma_f32 v[114:115], v[92:93], v[114:115], v[92:93] neg_lo:[1,0,0] neg_hi:[1,0,0]
	v_cmp_gt_f32_e32 vcc, 0, v93
	v_pk_mul_f32 v[120:121], v[94:95], v[116:117]
	v_pk_fma_f32 v[116:117], v[94:95], v[116:117], v[94:95] neg_lo:[1,0,0] neg_hi:[1,0,0]
	v_cmp_gt_f32_e64 s[0:1], 0, v94
	v_cmp_gt_f32_e64 s[4:5], 0, v95
	v_cmp_gt_f32_e64 s[6:7], 0, v92
	v_cndmask_b32_e32 v93, v115, v119, vcc
	v_cndmask_b32_e64 v94, v116, v120, s[0:1]
	v_cndmask_b32_e64 v92, v114, v118, s[6:7]
	v_cndmask_b32_e64 v95, v117, v121, s[4:5]
	v_mul_f32_e32 v72, v72, v92
	v_mul_f32_e32 v73, v73, v93
	v_mul_f32_e32 v74, v74, v94
	v_mul_f32_e32 v75, v75, v95
	v_cvt_pk_bf16_f32 v72, v72, v73
	v_cvt_pk_bf16_f32 v73, v74, v75
	v_mov_b64_e32 v[74:75], v[150:151]
	s_waitcnt lgkmcnt(0)
	v_mfma_f32_16x16x32_bf16 v[0:3], v[16:19], v[0:3], v[4:7]
	v_mov_b64_e32 v[250:251], v[72:73]
	v_lshlrev_b32_e32 v72, 16, v74
	v_and_b32_e32 v73, 0xffff0000, v74
	v_lshlrev_b32_e32 v74, 16, v75
	v_and_b32_e32 v75, 0xffff0000, v75
	v_and_b32_e32 v93, 0x7fffffff, v73
	v_and_b32_e32 v92, 0x7fffffff, v72
	v_and_b32_e32 v115, 0x7fffffff, v75
	v_and_b32_e32 v114, 0x7fffffff, v74
	v_pk_fma_f32 v[92:93], v[92:93], s[12:13], 1.0 op_sel_hi:[1,0,0]
	v_pk_fma_f32 v[114:115], v[114:115], s[12:13], 1.0 op_sel_hi:[1,0,0]
	v_rcp_f32_e32 v92, v92
	v_rcp_f32_e32 v93, v93
	v_rcp_f32_e32 v114, v114
	v_rcp_f32_e32 v115, v115
	v_pk_mul_f32 v[94:95], v[72:73], v[72:73]
	v_pk_mul_f32 v[116:117], v[74:75], v[74:75]
	v_pk_mul_f32 v[94:95], v[94:95], s[62:63] op_sel_hi:[1,0]
	v_pk_mul_f32 v[116:117], v[116:117], s[62:63] op_sel_hi:[1,0]
	v_pk_fma_f32 v[118:119], v[92:93], s[36:37], v[88:89] op_sel_hi:[1,0,0]
	v_pk_fma_f32 v[120:121], v[114:115], s[36:37], v[88:89] op_sel_hi:[1,0,0]
	v_exp_f32_e32 v94, v94
	v_exp_f32_e32 v95, v95
	v_exp_f32_e32 v116, v116
	v_exp_f32_e32 v117, v117
	v_pk_fma_f32 v[118:119], v[92:93], v[118:119], s[38:39] op_sel_hi:[1,1,0]
	v_pk_fma_f32 v[120:121], v[114:115], v[120:121], s[38:39] op_sel_hi:[1,1,0]
	v_pk_fma_f32 v[118:119], v[92:93], v[118:119], s[40:41] op_sel_hi:[1,1,0]
	v_pk_fma_f32 v[120:121], v[114:115], v[120:121], s[40:41] op_sel_hi:[1,1,0]
	v_pk_fma_f32 v[118:119], v[92:93], v[118:119], s[60:61] op_sel_hi:[1,1,0]
	v_pk_fma_f32 v[120:121], v[114:115], v[120:121], s[60:61] op_sel_hi:[1,1,0]
	v_pk_mul_f32 v[92:93], v[92:93], v[118:119]
	v_pk_mul_f32 v[114:115], v[114:115], v[120:121]
	v_pk_mul_f32 v[92:93], v[94:95], v[92:93]
	v_pk_mul_f32 v[94:95], v[116:117], v[114:115]
	v_pk_mul_f32 v[114:115], v[72:73], v[92:93]
	v_pk_fma_f32 v[92:93], v[72:73], v[92:93], v[72:73] neg_lo:[1,0,0] neg_hi:[1,0,0]
	v_cmp_gt_f32_e32 vcc, 0, v73
	v_pk_mul_f32 v[116:117], v[74:75], v[94:95]
	v_pk_fma_f32 v[94:95], v[74:75], v[94:95], v[74:75] neg_lo:[1,0,0] neg_hi:[1,0,0]
	v_cmp_gt_f32_e64 s[0:1], 0, v74
	v_cmp_gt_f32_e64 s[4:5], 0, v75
	v_cmp_gt_f32_e64 s[6:7], 0, v72
	v_cndmask_b32_e32 v73, v93, v115, vcc
	v_cndmask_b32_e64 v74, v94, v116, s[0:1]
	v_cndmask_b32_e64 v72, v92, v114, s[6:7]
	v_cndmask_b32_e64 v75, v95, v117, s[4:5]
	v_mul_f32_e32 v68, v68, v72
	v_mul_f32_e32 v69, v69, v73
	v_mul_f32_e32 v70, v70, v74
	v_mul_f32_e32 v71, v71, v75
	v_cvt_pk_bf16_f32 v68, v68, v69
	v_cvt_pk_bf16_f32 v69, v70, v71
	v_mov_b64_e32 v[70:71], v[152:153]
	v_add_f32_e32 v16, v113, v0
	v_mov_b64_e32 v[252:253], v[68:69]
	s_nop 1
	v_permlane16_swap_b32_e32 v250, v252
	v_permlane16_swap_b32_e32 v251, v253
	s_nop 1
	global_store_dwordx4 v[228:229], v[250:253], off offset:64
	v_add_f32_e32 v17, v113, v1
	v_add_f32_e32 v18, v113, v2
	v_add_f32_e32 v19, v113, v3
	v_lshlrev_b32_e32 v68, 16, v70
	v_and_b32_e32 v69, 0xffff0000, v70
	v_lshlrev_b32_e32 v70, 16, v71
	v_and_b32_e32 v71, 0xffff0000, v71
	v_and_b32_e32 v73, 0x7fffffff, v69
	v_and_b32_e32 v72, 0x7fffffff, v68
	v_and_b32_e32 v93, 0x7fffffff, v71
	v_and_b32_e32 v92, 0x7fffffff, v70
	v_pk_fma_f32 v[72:73], v[72:73], s[12:13], 1.0 op_sel_hi:[1,0,0]
	v_pk_fma_f32 v[92:93], v[92:93], s[12:13], 1.0 op_sel_hi:[1,0,0]
	v_rcp_f32_e32 v72, v72
	v_rcp_f32_e32 v73, v73
	v_rcp_f32_e32 v92, v92
	v_rcp_f32_e32 v93, v93
	v_pk_mul_f32 v[74:75], v[68:69], v[68:69]
	v_pk_mul_f32 v[94:95], v[70:71], v[70:71]
	v_pk_mul_f32 v[74:75], v[74:75], s[62:63] op_sel_hi:[1,0]
	v_pk_mul_f32 v[94:95], v[94:95], s[62:63] op_sel_hi:[1,0]
	v_pk_fma_f32 v[114:115], v[72:73], s[36:37], v[88:89] op_sel_hi:[1,0,0]
	v_pk_fma_f32 v[116:117], v[92:93], s[36:37], v[88:89] op_sel_hi:[1,0,0]
	v_exp_f32_e32 v74, v74
	v_exp_f32_e32 v75, v75
	v_exp_f32_e32 v94, v94
	v_exp_f32_e32 v95, v95
	v_pk_fma_f32 v[114:115], v[72:73], v[114:115], s[38:39] op_sel_hi:[1,1,0]
	v_pk_fma_f32 v[116:117], v[92:93], v[116:117], s[38:39] op_sel_hi:[1,1,0]
	v_pk_fma_f32 v[114:115], v[72:73], v[114:115], s[40:41] op_sel_hi:[1,1,0]
	v_pk_fma_f32 v[116:117], v[92:93], v[116:117], s[40:41] op_sel_hi:[1,1,0]
	v_pk_fma_f32 v[114:115], v[72:73], v[114:115], s[60:61] op_sel_hi:[1,1,0]
	v_pk_fma_f32 v[116:117], v[92:93], v[116:117], s[60:61] op_sel_hi:[1,1,0]
	v_pk_mul_f32 v[72:73], v[72:73], v[114:115]
	v_pk_mul_f32 v[92:93], v[92:93], v[116:117]
	v_pk_mul_f32 v[72:73], v[74:75], v[72:73]
	v_pk_mul_f32 v[74:75], v[94:95], v[92:93]
	v_pk_mul_f32 v[92:93], v[68:69], v[72:73]
	v_pk_fma_f32 v[72:73], v[68:69], v[72:73], v[68:69] neg_lo:[1,0,0] neg_hi:[1,0,0]
	v_cmp_gt_f32_e32 vcc, 0, v69
	v_pk_mul_f32 v[94:95], v[70:71], v[74:75]
	v_pk_fma_f32 v[74:75], v[70:71], v[74:75], v[70:71] neg_lo:[1,0,0] neg_hi:[1,0,0]
	v_cmp_gt_f32_e64 s[0:1], 0, v70
	v_cmp_gt_f32_e64 s[4:5], 0, v71
	v_cmp_gt_f32_e64 s[6:7], 0, v68
	v_cndmask_b32_e32 v69, v73, v93, vcc
	v_cndmask_b32_e64 v70, v74, v94, s[0:1]
	v_cndmask_b32_e64 v68, v72, v92, s[6:7]
	v_cndmask_b32_e64 v71, v75, v95, s[4:5]
	v_mul_f32_e32 v64, v64, v68
	v_mul_f32_e32 v65, v65, v69
	v_mul_f32_e32 v66, v66, v70
	v_mul_f32_e32 v67, v67, v71
	v_cvt_pk_bf16_f32 v64, v64, v65
	v_cvt_pk_bf16_f32 v65, v66, v67
	v_mov_b64_e32 v[66:67], v[154:155]
	s_nop 0
	v_mov_b64_e32 v[250:251], v[64:65]
	v_lshlrev_b32_e32 v64, 16, v66
	v_and_b32_e32 v65, 0xffff0000, v66
	v_lshlrev_b32_e32 v66, 16, v67
	v_and_b32_e32 v67, 0xffff0000, v67
	v_and_b32_e32 v69, 0x7fffffff, v65
	v_and_b32_e32 v68, 0x7fffffff, v64
	v_and_b32_e32 v73, 0x7fffffff, v67
	v_and_b32_e32 v72, 0x7fffffff, v66
	v_pk_fma_f32 v[68:69], v[68:69], s[12:13], 1.0 op_sel_hi:[1,0,0]
	v_pk_fma_f32 v[72:73], v[72:73], s[12:13], 1.0 op_sel_hi:[1,0,0]
	v_rcp_f32_e32 v68, v68
	v_rcp_f32_e32 v69, v69
	v_rcp_f32_e32 v72, v72
	v_rcp_f32_e32 v73, v73
	v_pk_mul_f32 v[70:71], v[64:65], v[64:65]
	v_pk_mul_f32 v[74:75], v[66:67], v[66:67]
	v_pk_mul_f32 v[70:71], v[70:71], s[62:63] op_sel_hi:[1,0]
	v_pk_mul_f32 v[74:75], v[74:75], s[62:63] op_sel_hi:[1,0]
	v_pk_fma_f32 v[92:93], v[68:69], s[36:37], v[88:89] op_sel_hi:[1,0,0]
	v_pk_fma_f32 v[94:95], v[72:73], s[36:37], v[88:89] op_sel_hi:[1,0,0]
	v_exp_f32_e32 v70, v70
	v_exp_f32_e32 v71, v71
	v_exp_f32_e32 v74, v74
	v_exp_f32_e32 v75, v75
	v_pk_fma_f32 v[92:93], v[68:69], v[92:93], s[38:39] op_sel_hi:[1,1,0]
	v_pk_fma_f32 v[94:95], v[72:73], v[94:95], s[38:39] op_sel_hi:[1,1,0]
	v_pk_fma_f32 v[92:93], v[68:69], v[92:93], s[40:41] op_sel_hi:[1,1,0]
	v_pk_fma_f32 v[94:95], v[72:73], v[94:95], s[40:41] op_sel_hi:[1,1,0]
	v_pk_fma_f32 v[92:93], v[68:69], v[92:93], s[60:61] op_sel_hi:[1,1,0]
	v_pk_fma_f32 v[94:95], v[72:73], v[94:95], s[60:61] op_sel_hi:[1,1,0]
	v_pk_mul_f32 v[68:69], v[68:69], v[92:93]
	v_pk_mul_f32 v[72:73], v[72:73], v[94:95]
	v_pk_mul_f32 v[68:69], v[70:71], v[68:69]
	v_pk_mul_f32 v[70:71], v[74:75], v[72:73]
	v_pk_mul_f32 v[72:73], v[64:65], v[68:69]
	v_pk_fma_f32 v[68:69], v[64:65], v[68:69], v[64:65] neg_lo:[1,0,0] neg_hi:[1,0,0]
	v_cmp_gt_f32_e32 vcc, 0, v65
	v_pk_mul_f32 v[74:75], v[66:67], v[70:71]
	v_pk_fma_f32 v[70:71], v[66:67], v[70:71], v[66:67] neg_lo:[1,0,0] neg_hi:[1,0,0]
	v_cmp_gt_f32_e64 s[0:1], 0, v66
	v_cmp_gt_f32_e64 s[4:5], 0, v67
	v_cmp_gt_f32_e64 s[6:7], 0, v64
	v_cndmask_b32_e32 v65, v69, v73, vcc
	v_cndmask_b32_e64 v66, v70, v74, s[0:1]
	v_cndmask_b32_e64 v64, v68, v72, s[6:7]
	v_cndmask_b32_e64 v67, v71, v75, s[4:5]
	v_mul_f32_e32 v60, v60, v64
	v_mul_f32_e32 v61, v61, v65
	v_mul_f32_e32 v62, v62, v66
	v_mul_f32_e32 v63, v63, v67
	v_cvt_pk_bf16_f32 v60, v60, v61
	v_cvt_pk_bf16_f32 v61, v62, v63
	v_mov_b64_e32 v[62:63], v[156:157]
	s_nop 0
	v_mov_b64_e32 v[252:253], v[60:61]
	s_nop 1
	v_permlane16_swap_b32_e32 v250, v252
	v_permlane16_swap_b32_e32 v251, v253
	s_nop 1
	global_store_dwordx4 v[228:229], v[250:253], off offset:128
	v_lshlrev_b32_e32 v60, 16, v62
	v_and_b32_e32 v61, 0xffff0000, v62
	v_lshlrev_b32_e32 v62, 16, v63
	v_and_b32_e32 v63, 0xffff0000, v63
	v_and_b32_e32 v65, 0x7fffffff, v61
	v_and_b32_e32 v64, 0x7fffffff, v60
	v_and_b32_e32 v69, 0x7fffffff, v63
	v_and_b32_e32 v68, 0x7fffffff, v62
	v_pk_fma_f32 v[64:65], v[64:65], s[12:13], 1.0 op_sel_hi:[1,0,0]
	v_pk_fma_f32 v[68:69], v[68:69], s[12:13], 1.0 op_sel_hi:[1,0,0]
	v_rcp_f32_e32 v64, v64
	v_rcp_f32_e32 v65, v65
	v_rcp_f32_e32 v68, v68
	v_rcp_f32_e32 v69, v69
	v_pk_mul_f32 v[66:67], v[60:61], v[60:61]
	v_pk_mul_f32 v[70:71], v[62:63], v[62:63]
	v_pk_mul_f32 v[66:67], v[66:67], s[62:63] op_sel_hi:[1,0]
	v_pk_mul_f32 v[70:71], v[70:71], s[62:63] op_sel_hi:[1,0]
	v_pk_fma_f32 v[72:73], v[64:65], s[36:37], v[88:89] op_sel_hi:[1,0,0]
	v_pk_fma_f32 v[74:75], v[68:69], s[36:37], v[88:89] op_sel_hi:[1,0,0]
	v_exp_f32_e32 v66, v66
	v_exp_f32_e32 v67, v67
	v_exp_f32_e32 v70, v70
	v_exp_f32_e32 v71, v71
	v_pk_fma_f32 v[72:73], v[64:65], v[72:73], s[38:39] op_sel_hi:[1,1,0]
	v_pk_fma_f32 v[74:75], v[68:69], v[74:75], s[38:39] op_sel_hi:[1,1,0]
	v_pk_fma_f32 v[72:73], v[64:65], v[72:73], s[40:41] op_sel_hi:[1,1,0]
	v_pk_fma_f32 v[74:75], v[68:69], v[74:75], s[40:41] op_sel_hi:[1,1,0]
	v_pk_fma_f32 v[72:73], v[64:65], v[72:73], s[60:61] op_sel_hi:[1,1,0]
	v_pk_fma_f32 v[74:75], v[68:69], v[74:75], s[60:61] op_sel_hi:[1,1,0]
	v_pk_mul_f32 v[64:65], v[64:65], v[72:73]
	v_pk_mul_f32 v[68:69], v[68:69], v[74:75]
	v_pk_mul_f32 v[64:65], v[66:67], v[64:65]
	v_pk_mul_f32 v[66:67], v[70:71], v[68:69]
	v_pk_mul_f32 v[68:69], v[60:61], v[64:65]
	v_pk_fma_f32 v[64:65], v[60:61], v[64:65], v[60:61] neg_lo:[1,0,0] neg_hi:[1,0,0]
	v_cmp_gt_f32_e32 vcc, 0, v61
	v_pk_mul_f32 v[70:71], v[62:63], v[66:67]
	v_pk_fma_f32 v[66:67], v[62:63], v[66:67], v[62:63] neg_lo:[1,0,0] neg_hi:[1,0,0]
	v_cmp_gt_f32_e64 s[0:1], 0, v62
	v_cmp_gt_f32_e64 s[4:5], 0, v63
	v_cmp_gt_f32_e64 s[6:7], 0, v60
	v_cndmask_b32_e32 v61, v65, v69, vcc
	v_cndmask_b32_e64 v62, v66, v70, s[0:1]
	v_cndmask_b32_e64 v60, v64, v68, s[6:7]
	v_cndmask_b32_e64 v63, v67, v71, s[4:5]
	v_mul_f32_e32 v56, v56, v60
	v_mul_f32_e32 v57, v57, v61
	v_mul_f32_e32 v58, v58, v62
	v_mul_f32_e32 v59, v59, v63
	v_cvt_pk_bf16_f32 v56, v56, v57
	v_cvt_pk_bf16_f32 v57, v58, v59
	v_mov_b64_e32 v[58:59], v[158:159]
	s_nop 0
	v_mov_b64_e32 v[250:251], v[56:57]
	v_lshlrev_b32_e32 v56, 16, v58
	v_and_b32_e32 v57, 0xffff0000, v58
	v_lshlrev_b32_e32 v58, 16, v59
	v_and_b32_e32 v59, 0xffff0000, v59
	v_and_b32_e32 v61, 0x7fffffff, v57
	v_and_b32_e32 v60, 0x7fffffff, v56
	v_and_b32_e32 v65, 0x7fffffff, v59
	v_and_b32_e32 v64, 0x7fffffff, v58
	v_pk_fma_f32 v[60:61], v[60:61], s[12:13], 1.0 op_sel_hi:[1,0,0]
	v_pk_fma_f32 v[64:65], v[64:65], s[12:13], 1.0 op_sel_hi:[1,0,0]
	v_rcp_f32_e32 v60, v60
	v_rcp_f32_e32 v61, v61
	v_rcp_f32_e32 v64, v64
	v_rcp_f32_e32 v65, v65
	v_pk_mul_f32 v[62:63], v[56:57], v[56:57]
	v_pk_mul_f32 v[66:67], v[58:59], v[58:59]
	v_pk_mul_f32 v[62:63], v[62:63], s[62:63] op_sel_hi:[1,0]
	v_pk_mul_f32 v[66:67], v[66:67], s[62:63] op_sel_hi:[1,0]
	v_pk_fma_f32 v[68:69], v[60:61], s[36:37], v[88:89] op_sel_hi:[1,0,0]
	v_pk_fma_f32 v[70:71], v[64:65], s[36:37], v[88:89] op_sel_hi:[1,0,0]
	v_exp_f32_e32 v62, v62
	v_exp_f32_e32 v63, v63
	v_exp_f32_e32 v66, v66
	v_exp_f32_e32 v67, v67
	v_pk_fma_f32 v[68:69], v[60:61], v[68:69], s[38:39] op_sel_hi:[1,1,0]
	v_pk_fma_f32 v[70:71], v[64:65], v[70:71], s[38:39] op_sel_hi:[1,1,0]
	v_pk_fma_f32 v[68:69], v[60:61], v[68:69], s[40:41] op_sel_hi:[1,1,0]
	v_pk_fma_f32 v[70:71], v[64:65], v[70:71], s[40:41] op_sel_hi:[1,1,0]
	v_pk_fma_f32 v[68:69], v[60:61], v[68:69], s[60:61] op_sel_hi:[1,1,0]
	v_pk_fma_f32 v[70:71], v[64:65], v[70:71], s[60:61] op_sel_hi:[1,1,0]
	v_pk_mul_f32 v[60:61], v[60:61], v[68:69]
	v_pk_mul_f32 v[64:65], v[64:65], v[70:71]
	v_pk_mul_f32 v[60:61], v[62:63], v[60:61]
	v_pk_mul_f32 v[62:63], v[66:67], v[64:65]
	v_pk_mul_f32 v[64:65], v[56:57], v[60:61]
	v_pk_fma_f32 v[60:61], v[56:57], v[60:61], v[56:57] neg_lo:[1,0,0] neg_hi:[1,0,0]
	v_cmp_gt_f32_e32 vcc, 0, v57
	v_pk_mul_f32 v[66:67], v[58:59], v[62:63]
	v_pk_fma_f32 v[62:63], v[58:59], v[62:63], v[58:59] neg_lo:[1,0,0] neg_hi:[1,0,0]
	v_cmp_gt_f32_e64 s[0:1], 0, v58
	v_cmp_gt_f32_e64 s[4:5], 0, v59
	v_cmp_gt_f32_e64 s[6:7], 0, v56
	v_cndmask_b32_e32 v57, v61, v65, vcc
	v_cndmask_b32_e64 v58, v62, v66, s[0:1]
	v_cndmask_b32_e64 v56, v60, v64, s[6:7]
	v_cndmask_b32_e64 v59, v63, v67, s[4:5]
	v_mul_f32_e32 v52, v52, v56
	v_mul_f32_e32 v53, v53, v57
	v_mul_f32_e32 v54, v54, v58
	v_mul_f32_e32 v55, v55, v59
	v_cvt_pk_bf16_f32 v52, v52, v53
	v_cvt_pk_bf16_f32 v53, v54, v55
	v_mov_b64_e32 v[54:55], v[160:161]
	s_nop 0
	v_mov_b64_e32 v[252:253], v[52:53]
	s_nop 1
	v_permlane16_swap_b32_e32 v250, v252
	v_permlane16_swap_b32_e32 v251, v253
	s_nop 1
	global_store_dwordx4 v[228:229], v[250:253], off offset:192
	v_lshlrev_b32_e32 v52, 16, v54
	v_and_b32_e32 v53, 0xffff0000, v54
	v_lshlrev_b32_e32 v54, 16, v55
	v_and_b32_e32 v55, 0xffff0000, v55
	v_and_b32_e32 v57, 0x7fffffff, v53
	v_and_b32_e32 v56, 0x7fffffff, v52
	v_and_b32_e32 v61, 0x7fffffff, v55
	v_and_b32_e32 v60, 0x7fffffff, v54
	v_pk_fma_f32 v[56:57], v[56:57], s[12:13], 1.0 op_sel_hi:[1,0,0]
	v_pk_fma_f32 v[60:61], v[60:61], s[12:13], 1.0 op_sel_hi:[1,0,0]
	v_rcp_f32_e32 v56, v56
	v_rcp_f32_e32 v57, v57
	v_rcp_f32_e32 v60, v60
	v_rcp_f32_e32 v61, v61
	v_pk_mul_f32 v[58:59], v[52:53], v[52:53]
	v_pk_mul_f32 v[62:63], v[54:55], v[54:55]
	v_pk_mul_f32 v[58:59], v[58:59], s[62:63] op_sel_hi:[1,0]
	v_pk_mul_f32 v[62:63], v[62:63], s[62:63] op_sel_hi:[1,0]
	v_pk_fma_f32 v[64:65], v[56:57], s[36:37], v[88:89] op_sel_hi:[1,0,0]
	v_pk_fma_f32 v[66:67], v[60:61], s[36:37], v[88:89] op_sel_hi:[1,0,0]
	v_exp_f32_e32 v58, v58
	v_exp_f32_e32 v59, v59
	v_exp_f32_e32 v62, v62
	v_exp_f32_e32 v63, v63
	v_pk_fma_f32 v[64:65], v[56:57], v[64:65], s[38:39] op_sel_hi:[1,1,0]
	v_pk_fma_f32 v[66:67], v[60:61], v[66:67], s[38:39] op_sel_hi:[1,1,0]
	v_pk_fma_f32 v[64:65], v[56:57], v[64:65], s[40:41] op_sel_hi:[1,1,0]
	v_pk_fma_f32 v[66:67], v[60:61], v[66:67], s[40:41] op_sel_hi:[1,1,0]
	v_pk_fma_f32 v[64:65], v[56:57], v[64:65], s[60:61] op_sel_hi:[1,1,0]
	v_pk_fma_f32 v[66:67], v[60:61], v[66:67], s[60:61] op_sel_hi:[1,1,0]
	v_pk_mul_f32 v[56:57], v[56:57], v[64:65]
	v_pk_mul_f32 v[60:61], v[60:61], v[66:67]
	v_pk_mul_f32 v[56:57], v[58:59], v[56:57]
	v_pk_mul_f32 v[58:59], v[62:63], v[60:61]
	v_pk_mul_f32 v[60:61], v[52:53], v[56:57]
	v_pk_fma_f32 v[56:57], v[52:53], v[56:57], v[52:53] neg_lo:[1,0,0] neg_hi:[1,0,0]
	v_cmp_gt_f32_e32 vcc, 0, v53
	v_pk_mul_f32 v[62:63], v[54:55], v[58:59]
	v_pk_fma_f32 v[58:59], v[54:55], v[58:59], v[54:55] neg_lo:[1,0,0] neg_hi:[1,0,0]
	v_cmp_gt_f32_e64 s[0:1], 0, v54
	v_cmp_gt_f32_e64 s[4:5], 0, v55
	v_cmp_gt_f32_e64 s[6:7], 0, v52
	v_cndmask_b32_e32 v53, v57, v61, vcc
	v_cndmask_b32_e64 v54, v58, v62, s[0:1]
	v_cndmask_b32_e64 v52, v56, v60, s[6:7]
	v_cndmask_b32_e64 v55, v59, v63, s[4:5]
	v_mul_f32_e32 v48, v48, v52
	v_mul_f32_e32 v49, v49, v53
	v_mul_f32_e32 v50, v50, v54
	v_mul_f32_e32 v51, v51, v55
	v_cvt_pk_bf16_f32 v48, v48, v49
	v_cvt_pk_bf16_f32 v49, v50, v51
	v_mov_b64_e32 v[50:51], v[162:163]
	s_nop 0
	v_mov_b64_e32 v[250:251], v[48:49]
	v_lshlrev_b32_e32 v48, 16, v50
	v_and_b32_e32 v49, 0xffff0000, v50
	v_lshlrev_b32_e32 v50, 16, v51
	v_and_b32_e32 v51, 0xffff0000, v51
	v_and_b32_e32 v53, 0x7fffffff, v49
	v_and_b32_e32 v52, 0x7fffffff, v48
	v_and_b32_e32 v57, 0x7fffffff, v51
	v_and_b32_e32 v56, 0x7fffffff, v50
	v_pk_fma_f32 v[52:53], v[52:53], s[12:13], 1.0 op_sel_hi:[1,0,0]
	v_pk_fma_f32 v[56:57], v[56:57], s[12:13], 1.0 op_sel_hi:[1,0,0]
	v_rcp_f32_e32 v52, v52
	v_rcp_f32_e32 v53, v53
	v_rcp_f32_e32 v56, v56
	v_rcp_f32_e32 v57, v57
	v_pk_mul_f32 v[54:55], v[48:49], v[48:49]
	v_pk_mul_f32 v[58:59], v[50:51], v[50:51]
	v_pk_mul_f32 v[54:55], v[54:55], s[62:63] op_sel_hi:[1,0]
	v_pk_mul_f32 v[58:59], v[58:59], s[62:63] op_sel_hi:[1,0]
	v_pk_fma_f32 v[60:61], v[52:53], s[36:37], v[88:89] op_sel_hi:[1,0,0]
	v_pk_fma_f32 v[62:63], v[56:57], s[36:37], v[88:89] op_sel_hi:[1,0,0]
	v_exp_f32_e32 v54, v54
	v_exp_f32_e32 v55, v55
	v_exp_f32_e32 v58, v58
	v_exp_f32_e32 v59, v59
	v_pk_fma_f32 v[60:61], v[52:53], v[60:61], s[38:39] op_sel_hi:[1,1,0]
	v_pk_fma_f32 v[62:63], v[56:57], v[62:63], s[38:39] op_sel_hi:[1,1,0]
	v_pk_fma_f32 v[60:61], v[52:53], v[60:61], s[40:41] op_sel_hi:[1,1,0]
	v_pk_fma_f32 v[62:63], v[56:57], v[62:63], s[40:41] op_sel_hi:[1,1,0]
	v_pk_fma_f32 v[60:61], v[52:53], v[60:61], s[60:61] op_sel_hi:[1,1,0]
	v_pk_fma_f32 v[62:63], v[56:57], v[62:63], s[60:61] op_sel_hi:[1,1,0]
	v_pk_mul_f32 v[52:53], v[52:53], v[60:61]
	v_pk_mul_f32 v[56:57], v[56:57], v[62:63]
	v_pk_mul_f32 v[52:53], v[54:55], v[52:53]
	v_pk_mul_f32 v[54:55], v[58:59], v[56:57]
	v_pk_mul_f32 v[56:57], v[48:49], v[52:53]
	v_pk_fma_f32 v[52:53], v[48:49], v[52:53], v[48:49] neg_lo:[1,0,0] neg_hi:[1,0,0]
	v_cmp_gt_f32_e32 vcc, 0, v49
	v_pk_mul_f32 v[58:59], v[50:51], v[54:55]
	v_pk_fma_f32 v[54:55], v[50:51], v[54:55], v[50:51] neg_lo:[1,0,0] neg_hi:[1,0,0]
	v_cmp_gt_f32_e64 s[0:1], 0, v50
	v_cmp_gt_f32_e64 s[4:5], 0, v51
	v_cmp_gt_f32_e64 s[6:7], 0, v48
	v_cndmask_b32_e32 v49, v53, v57, vcc
	v_cndmask_b32_e64 v50, v54, v58, s[0:1]
	v_cndmask_b32_e64 v48, v52, v56, s[6:7]
	v_cndmask_b32_e64 v51, v55, v59, s[4:5]
	v_mul_f32_e32 v44, v44, v48
	v_mul_f32_e32 v45, v45, v49
	v_mul_f32_e32 v46, v46, v50
	v_mul_f32_e32 v47, v47, v51
	v_cvt_pk_bf16_f32 v44, v44, v45
	v_cvt_pk_bf16_f32 v45, v46, v47
	v_mov_b64_e32 v[46:47], v[164:165]
	s_nop 0
	v_mov_b64_e32 v[252:253], v[44:45]
	s_nop 1
	v_permlane16_swap_b32_e32 v250, v252
	v_permlane16_swap_b32_e32 v251, v253
	s_nop 1
	global_store_dwordx4 v[228:229], v[250:253], off offset:256
	v_lshlrev_b32_e32 v44, 16, v46
	v_and_b32_e32 v45, 0xffff0000, v46
	v_lshlrev_b32_e32 v46, 16, v47
	v_and_b32_e32 v47, 0xffff0000, v47
	v_and_b32_e32 v49, 0x7fffffff, v45
	v_and_b32_e32 v48, 0x7fffffff, v44
	v_and_b32_e32 v53, 0x7fffffff, v47
	v_and_b32_e32 v52, 0x7fffffff, v46
	v_pk_fma_f32 v[48:49], v[48:49], s[12:13], 1.0 op_sel_hi:[1,0,0]
	v_pk_fma_f32 v[52:53], v[52:53], s[12:13], 1.0 op_sel_hi:[1,0,0]
	v_rcp_f32_e32 v48, v48
	v_rcp_f32_e32 v49, v49
	v_rcp_f32_e32 v52, v52
	v_rcp_f32_e32 v53, v53
	v_pk_mul_f32 v[50:51], v[44:45], v[44:45]
	v_pk_mul_f32 v[54:55], v[46:47], v[46:47]
	v_pk_mul_f32 v[50:51], v[50:51], s[62:63] op_sel_hi:[1,0]
	v_pk_mul_f32 v[54:55], v[54:55], s[62:63] op_sel_hi:[1,0]
	v_pk_fma_f32 v[56:57], v[48:49], s[36:37], v[88:89] op_sel_hi:[1,0,0]
	v_pk_fma_f32 v[58:59], v[52:53], s[36:37], v[88:89] op_sel_hi:[1,0,0]
	v_exp_f32_e32 v50, v50
	v_exp_f32_e32 v51, v51
	v_exp_f32_e32 v54, v54
	v_exp_f32_e32 v55, v55
	v_pk_fma_f32 v[56:57], v[48:49], v[56:57], s[38:39] op_sel_hi:[1,1,0]
	v_pk_fma_f32 v[58:59], v[52:53], v[58:59], s[38:39] op_sel_hi:[1,1,0]
	v_pk_fma_f32 v[56:57], v[48:49], v[56:57], s[40:41] op_sel_hi:[1,1,0]
	v_pk_fma_f32 v[58:59], v[52:53], v[58:59], s[40:41] op_sel_hi:[1,1,0]
	v_pk_fma_f32 v[56:57], v[48:49], v[56:57], s[60:61] op_sel_hi:[1,1,0]
	v_pk_fma_f32 v[58:59], v[52:53], v[58:59], s[60:61] op_sel_hi:[1,1,0]
	v_pk_mul_f32 v[48:49], v[48:49], v[56:57]
	v_pk_mul_f32 v[52:53], v[52:53], v[58:59]
	v_pk_mul_f32 v[48:49], v[50:51], v[48:49]
	v_pk_mul_f32 v[50:51], v[54:55], v[52:53]
	v_pk_mul_f32 v[52:53], v[44:45], v[48:49]
	v_pk_fma_f32 v[48:49], v[44:45], v[48:49], v[44:45] neg_lo:[1,0,0] neg_hi:[1,0,0]
	v_cmp_gt_f32_e32 vcc, 0, v45
	v_pk_mul_f32 v[54:55], v[46:47], v[50:51]
	v_pk_fma_f32 v[50:51], v[46:47], v[50:51], v[46:47] neg_lo:[1,0,0] neg_hi:[1,0,0]
	v_cmp_gt_f32_e64 s[0:1], 0, v46
	v_cmp_gt_f32_e64 s[4:5], 0, v47
	v_cmp_gt_f32_e64 s[6:7], 0, v44
	v_cndmask_b32_e32 v45, v49, v53, vcc
	v_cndmask_b32_e64 v46, v50, v54, s[0:1]
	v_cndmask_b32_e64 v44, v48, v52, s[6:7]
	v_cndmask_b32_e64 v47, v51, v55, s[4:5]
	v_mul_f32_e32 v40, v40, v44
	v_mul_f32_e32 v41, v41, v45
	v_mul_f32_e32 v42, v42, v46
	v_mul_f32_e32 v43, v43, v47
	v_cvt_pk_bf16_f32 v40, v40, v41
	v_cvt_pk_bf16_f32 v41, v42, v43
	v_mov_b64_e32 v[42:43], v[166:167]
	s_nop 0
	v_mov_b64_e32 v[250:251], v[40:41]
	v_lshlrev_b32_e32 v40, 16, v42
	v_and_b32_e32 v41, 0xffff0000, v42
	v_lshlrev_b32_e32 v42, 16, v43
	v_and_b32_e32 v43, 0xffff0000, v43
	v_and_b32_e32 v45, 0x7fffffff, v41
	v_and_b32_e32 v44, 0x7fffffff, v40
	v_and_b32_e32 v49, 0x7fffffff, v43
	v_and_b32_e32 v48, 0x7fffffff, v42
	v_pk_fma_f32 v[44:45], v[44:45], s[12:13], 1.0 op_sel_hi:[1,0,0]
	v_pk_fma_f32 v[48:49], v[48:49], s[12:13], 1.0 op_sel_hi:[1,0,0]
	v_rcp_f32_e32 v44, v44
	v_rcp_f32_e32 v45, v45
	v_rcp_f32_e32 v48, v48
	v_rcp_f32_e32 v49, v49
	v_pk_mul_f32 v[46:47], v[40:41], v[40:41]
	v_pk_mul_f32 v[50:51], v[42:43], v[42:43]
	v_pk_mul_f32 v[46:47], v[46:47], s[62:63] op_sel_hi:[1,0]
	v_pk_mul_f32 v[50:51], v[50:51], s[62:63] op_sel_hi:[1,0]
	v_pk_fma_f32 v[52:53], v[44:45], s[36:37], v[88:89] op_sel_hi:[1,0,0]
	v_pk_fma_f32 v[54:55], v[48:49], s[36:37], v[88:89] op_sel_hi:[1,0,0]
	v_exp_f32_e32 v46, v46
	v_exp_f32_e32 v47, v47
	v_exp_f32_e32 v50, v50
	v_exp_f32_e32 v51, v51
	v_pk_fma_f32 v[52:53], v[44:45], v[52:53], s[38:39] op_sel_hi:[1,1,0]
	v_pk_fma_f32 v[54:55], v[48:49], v[54:55], s[38:39] op_sel_hi:[1,1,0]
	v_pk_fma_f32 v[52:53], v[44:45], v[52:53], s[40:41] op_sel_hi:[1,1,0]
	v_pk_fma_f32 v[54:55], v[48:49], v[54:55], s[40:41] op_sel_hi:[1,1,0]
	v_pk_fma_f32 v[52:53], v[44:45], v[52:53], s[60:61] op_sel_hi:[1,1,0]
	v_pk_fma_f32 v[54:55], v[48:49], v[54:55], s[60:61] op_sel_hi:[1,1,0]
	v_pk_mul_f32 v[44:45], v[44:45], v[52:53]
	v_pk_mul_f32 v[48:49], v[48:49], v[54:55]
	v_pk_mul_f32 v[44:45], v[46:47], v[44:45]
	v_pk_mul_f32 v[46:47], v[50:51], v[48:49]
	v_pk_mul_f32 v[48:49], v[40:41], v[44:45]
	v_pk_fma_f32 v[44:45], v[40:41], v[44:45], v[40:41] neg_lo:[1,0,0] neg_hi:[1,0,0]
	v_cmp_gt_f32_e32 vcc, 0, v41
	v_pk_mul_f32 v[50:51], v[42:43], v[46:47]
	v_pk_fma_f32 v[46:47], v[42:43], v[46:47], v[42:43] neg_lo:[1,0,0] neg_hi:[1,0,0]
	v_cmp_gt_f32_e64 s[0:1], 0, v42
	v_cmp_gt_f32_e64 s[4:5], 0, v43
	v_cmp_gt_f32_e64 s[6:7], 0, v40
	v_cndmask_b32_e32 v41, v45, v49, vcc
	v_cndmask_b32_e64 v42, v46, v50, s[0:1]
	v_cndmask_b32_e64 v40, v44, v48, s[6:7]
	v_cndmask_b32_e64 v43, v47, v51, s[4:5]
	v_mul_f32_e32 v36, v36, v40
	v_mul_f32_e32 v37, v37, v41
	v_mul_f32_e32 v38, v38, v42
	v_mul_f32_e32 v39, v39, v43
	v_cvt_pk_bf16_f32 v36, v36, v37
	v_cvt_pk_bf16_f32 v37, v38, v39
	v_mov_b64_e32 v[38:39], v[168:169]
	s_nop 0
	v_mov_b64_e32 v[252:253], v[36:37]
	s_nop 1
	v_permlane16_swap_b32_e32 v250, v252
	v_permlane16_swap_b32_e32 v251, v253
	s_nop 1
	global_store_dwordx4 v[228:229], v[250:253], off offset:320
	v_lshlrev_b32_e32 v36, 16, v38
	v_and_b32_e32 v37, 0xffff0000, v38
	v_lshlrev_b32_e32 v38, 16, v39
	v_and_b32_e32 v39, 0xffff0000, v39
	v_and_b32_e32 v41, 0x7fffffff, v37
	v_and_b32_e32 v40, 0x7fffffff, v36
	v_and_b32_e32 v45, 0x7fffffff, v39
	v_and_b32_e32 v44, 0x7fffffff, v38
	v_pk_fma_f32 v[40:41], v[40:41], s[12:13], 1.0 op_sel_hi:[1,0,0]
	v_pk_fma_f32 v[44:45], v[44:45], s[12:13], 1.0 op_sel_hi:[1,0,0]
	v_rcp_f32_e32 v40, v40
	v_rcp_f32_e32 v41, v41
	v_rcp_f32_e32 v44, v44
	v_rcp_f32_e32 v45, v45
	v_pk_mul_f32 v[42:43], v[36:37], v[36:37]
	v_pk_mul_f32 v[46:47], v[38:39], v[38:39]
	v_pk_mul_f32 v[42:43], v[42:43], s[62:63] op_sel_hi:[1,0]
	v_pk_mul_f32 v[46:47], v[46:47], s[62:63] op_sel_hi:[1,0]
	v_pk_fma_f32 v[48:49], v[40:41], s[36:37], v[88:89] op_sel_hi:[1,0,0]
	v_pk_fma_f32 v[50:51], v[44:45], s[36:37], v[88:89] op_sel_hi:[1,0,0]
	v_exp_f32_e32 v42, v42
	v_exp_f32_e32 v43, v43
	v_exp_f32_e32 v46, v46
	v_exp_f32_e32 v47, v47
	v_pk_fma_f32 v[48:49], v[40:41], v[48:49], s[38:39] op_sel_hi:[1,1,0]
	v_pk_fma_f32 v[50:51], v[44:45], v[50:51], s[38:39] op_sel_hi:[1,1,0]
	v_pk_fma_f32 v[48:49], v[40:41], v[48:49], s[40:41] op_sel_hi:[1,1,0]
	v_pk_fma_f32 v[50:51], v[44:45], v[50:51], s[40:41] op_sel_hi:[1,1,0]
	v_pk_fma_f32 v[48:49], v[40:41], v[48:49], s[60:61] op_sel_hi:[1,1,0]
	v_pk_fma_f32 v[50:51], v[44:45], v[50:51], s[60:61] op_sel_hi:[1,1,0]
	v_pk_mul_f32 v[40:41], v[40:41], v[48:49]
	v_pk_mul_f32 v[44:45], v[44:45], v[50:51]
	v_pk_mul_f32 v[40:41], v[42:43], v[40:41]
	v_pk_mul_f32 v[42:43], v[46:47], v[44:45]
	v_pk_mul_f32 v[44:45], v[36:37], v[40:41]
	v_pk_fma_f32 v[40:41], v[36:37], v[40:41], v[36:37] neg_lo:[1,0,0] neg_hi:[1,0,0]
	v_cmp_gt_f32_e32 vcc, 0, v37
	v_pk_mul_f32 v[46:47], v[38:39], v[42:43]
	v_pk_fma_f32 v[42:43], v[38:39], v[42:43], v[38:39] neg_lo:[1,0,0] neg_hi:[1,0,0]
	v_cmp_gt_f32_e64 s[0:1], 0, v38
	v_cmp_gt_f32_e64 s[4:5], 0, v39
	v_cmp_gt_f32_e64 s[6:7], 0, v36
	v_cndmask_b32_e32 v37, v41, v45, vcc
	v_cndmask_b32_e64 v38, v42, v46, s[0:1]
	v_cndmask_b32_e64 v36, v40, v44, s[6:7]
	v_cndmask_b32_e64 v39, v43, v47, s[4:5]
	v_mul_f32_e32 v32, v32, v36
	v_mul_f32_e32 v33, v33, v37
	v_mul_f32_e32 v34, v34, v38
	v_mul_f32_e32 v35, v35, v39
	v_cvt_pk_bf16_f32 v32, v32, v33
	v_cvt_pk_bf16_f32 v33, v34, v35
	v_mov_b64_e32 v[34:35], v[170:171]
	s_nop 0
	v_mov_b64_e32 v[250:251], v[32:33]
	v_lshlrev_b32_e32 v32, 16, v34
	v_and_b32_e32 v33, 0xffff0000, v34
	v_lshlrev_b32_e32 v34, 16, v35
	v_and_b32_e32 v35, 0xffff0000, v35
	v_and_b32_e32 v37, 0x7fffffff, v33
	v_and_b32_e32 v36, 0x7fffffff, v32
	v_and_b32_e32 v41, 0x7fffffff, v35
	v_and_b32_e32 v40, 0x7fffffff, v34
	v_pk_fma_f32 v[36:37], v[36:37], s[12:13], 1.0 op_sel_hi:[1,0,0]
	v_pk_fma_f32 v[40:41], v[40:41], s[12:13], 1.0 op_sel_hi:[1,0,0]
	v_rcp_f32_e32 v36, v36
	v_rcp_f32_e32 v37, v37
	v_rcp_f32_e32 v40, v40
	v_rcp_f32_e32 v41, v41
	v_pk_mul_f32 v[38:39], v[32:33], v[32:33]
	v_pk_mul_f32 v[42:43], v[34:35], v[34:35]
	v_pk_mul_f32 v[38:39], v[38:39], s[62:63] op_sel_hi:[1,0]
	v_pk_mul_f32 v[42:43], v[42:43], s[62:63] op_sel_hi:[1,0]
	v_pk_fma_f32 v[44:45], v[36:37], s[36:37], v[88:89] op_sel_hi:[1,0,0]
	v_pk_fma_f32 v[46:47], v[40:41], s[36:37], v[88:89] op_sel_hi:[1,0,0]
	v_exp_f32_e32 v38, v38
	v_exp_f32_e32 v39, v39
	v_exp_f32_e32 v42, v42
	v_exp_f32_e32 v43, v43
	v_pk_fma_f32 v[44:45], v[36:37], v[44:45], s[38:39] op_sel_hi:[1,1,0]
	v_pk_fma_f32 v[46:47], v[40:41], v[46:47], s[38:39] op_sel_hi:[1,1,0]
	v_pk_fma_f32 v[44:45], v[36:37], v[44:45], s[40:41] op_sel_hi:[1,1,0]
	v_pk_fma_f32 v[46:47], v[40:41], v[46:47], s[40:41] op_sel_hi:[1,1,0]
	v_pk_fma_f32 v[44:45], v[36:37], v[44:45], s[60:61] op_sel_hi:[1,1,0]
	v_pk_fma_f32 v[46:47], v[40:41], v[46:47], s[60:61] op_sel_hi:[1,1,0]
	v_pk_mul_f32 v[36:37], v[36:37], v[44:45]
	v_pk_mul_f32 v[40:41], v[40:41], v[46:47]
	v_pk_mul_f32 v[36:37], v[38:39], v[36:37]
	v_pk_mul_f32 v[38:39], v[42:43], v[40:41]
	v_pk_mul_f32 v[40:41], v[32:33], v[36:37]
	v_pk_fma_f32 v[36:37], v[32:33], v[36:37], v[32:33] neg_lo:[1,0,0] neg_hi:[1,0,0]
	v_cmp_gt_f32_e32 vcc, 0, v33
	v_pk_mul_f32 v[42:43], v[34:35], v[38:39]
	v_pk_fma_f32 v[38:39], v[34:35], v[38:39], v[34:35] neg_lo:[1,0,0] neg_hi:[1,0,0]
	v_cmp_gt_f32_e64 s[0:1], 0, v34
	v_cmp_gt_f32_e64 s[4:5], 0, v35
	v_cmp_gt_f32_e64 s[6:7], 0, v32
	v_cndmask_b32_e32 v33, v37, v41, vcc
	v_cndmask_b32_e64 v34, v38, v42, s[0:1]
	v_cndmask_b32_e64 v32, v36, v40, s[6:7]
	v_cndmask_b32_e64 v35, v39, v43, s[4:5]
	v_mul_f32_e32 v28, v28, v32
	v_mul_f32_e32 v29, v29, v33
	v_mul_f32_e32 v30, v30, v34
	v_mul_f32_e32 v31, v31, v35
	v_cvt_pk_bf16_f32 v28, v28, v29
	v_cvt_pk_bf16_f32 v29, v30, v31
	v_mov_b64_e32 v[30:31], v[172:173]
	v_add_f32_e32 v36, v20, v113
	v_add_f32_e32 v37, v21, v113
	v_add_f32_e32 v38, v22, v113
	v_add_f32_e32 v39, v23, v113
	v_mov_b64_e32 v[252:253], v[28:29]
	s_nop 1
	v_permlane16_swap_b32_e32 v250, v252
	v_permlane16_swap_b32_e32 v251, v253
	s_nop 1
	global_store_dwordx4 v[228:229], v[250:253], off offset:384
	v_lshlrev_b32_e32 v20, 16, v30
	v_and_b32_e32 v21, 0xffff0000, v30
	v_lshlrev_b32_e32 v22, 16, v31
	v_and_b32_e32 v23, 0xffff0000, v31
	v_and_b32_e32 v25, 0x7fffffff, v21
	v_and_b32_e32 v24, 0x7fffffff, v20
	v_and_b32_e32 v29, 0x7fffffff, v23
	v_and_b32_e32 v28, 0x7fffffff, v22
	v_pk_fma_f32 v[24:25], v[24:25], s[12:13], 1.0 op_sel_hi:[1,0,0]
	v_pk_fma_f32 v[28:29], v[28:29], s[12:13], 1.0 op_sel_hi:[1,0,0]
	v_rcp_f32_e32 v24, v24
	v_rcp_f32_e32 v25, v25
	v_rcp_f32_e32 v28, v28
	v_rcp_f32_e32 v29, v29
	v_pk_mul_f32 v[26:27], v[20:21], v[20:21]
	v_pk_mul_f32 v[30:31], v[22:23], v[22:23]
	v_pk_mul_f32 v[26:27], v[26:27], s[62:63] op_sel_hi:[1,0]
	v_pk_mul_f32 v[30:31], v[30:31], s[62:63] op_sel_hi:[1,0]
	v_pk_fma_f32 v[32:33], v[24:25], s[36:37], v[88:89] op_sel_hi:[1,0,0]
	v_pk_fma_f32 v[34:35], v[28:29], s[36:37], v[88:89] op_sel_hi:[1,0,0]
	v_exp_f32_e32 v26, v26
	v_exp_f32_e32 v27, v27
	v_exp_f32_e32 v30, v30
	v_exp_f32_e32 v31, v31
	v_pk_fma_f32 v[32:33], v[24:25], v[32:33], s[38:39] op_sel_hi:[1,1,0]
	v_pk_fma_f32 v[34:35], v[28:29], v[34:35], s[38:39] op_sel_hi:[1,1,0]
	v_pk_fma_f32 v[32:33], v[24:25], v[32:33], s[40:41] op_sel_hi:[1,1,0]
	v_pk_fma_f32 v[34:35], v[28:29], v[34:35], s[40:41] op_sel_hi:[1,1,0]
	v_pk_fma_f32 v[32:33], v[24:25], v[32:33], s[60:61] op_sel_hi:[1,1,0]
	v_pk_fma_f32 v[34:35], v[28:29], v[34:35], s[60:61] op_sel_hi:[1,1,0]
	v_pk_mul_f32 v[24:25], v[24:25], v[32:33]
	v_pk_mul_f32 v[28:29], v[28:29], v[34:35]
	v_pk_mul_f32 v[24:25], v[26:27], v[24:25]
	v_pk_mul_f32 v[26:27], v[30:31], v[28:29]
	v_pk_mul_f32 v[28:29], v[20:21], v[24:25]
	v_pk_fma_f32 v[24:25], v[20:21], v[24:25], v[20:21] neg_lo:[1,0,0] neg_hi:[1,0,0]
	v_cmp_gt_f32_e32 vcc, 0, v21
	v_pk_mul_f32 v[30:31], v[22:23], v[26:27]
	v_pk_fma_f32 v[26:27], v[22:23], v[26:27], v[22:23] neg_lo:[1,0,0] neg_hi:[1,0,0]
	v_cmp_gt_f32_e64 s[0:1], 0, v22
	v_cmp_gt_f32_e64 s[4:5], 0, v23
	v_cmp_gt_f32_e64 s[6:7], 0, v20
	v_cndmask_b32_e32 v21, v25, v29, vcc
	v_cndmask_b32_e64 v22, v26, v30, s[0:1]
	v_cndmask_b32_e64 v20, v24, v28, s[6:7]
	v_cndmask_b32_e64 v23, v27, v31, s[4:5]
	v_mul_f32_e32 v20, v36, v20
	v_mul_f32_e32 v21, v37, v21
	v_mul_f32_e32 v22, v38, v22
	v_mul_f32_e32 v23, v39, v23
	v_cvt_pk_bf16_f32 v20, v20, v21
	v_cvt_pk_bf16_f32 v21, v22, v23
	v_mov_b64_e32 v[22:23], v[174:175]
	s_add_i32 s13, s13, s30
	s_cmpk_lt_i32 s13, 0x200
	v_mov_b64_e32 v[250:251], v[20:21]
	v_lshlrev_b32_e32 v0, 16, v22
	v_and_b32_e32 v1, 0xffff0000, v22
	v_lshlrev_b32_e32 v2, 16, v23
	v_and_b32_e32 v3, 0xffff0000, v23
	v_and_b32_e32 v5, 0x7fffffff, v1
	v_and_b32_e32 v4, 0x7fffffff, v0
	v_and_b32_e32 v9, 0x7fffffff, v3
	v_and_b32_e32 v8, 0x7fffffff, v2
	v_pk_fma_f32 v[4:5], v[4:5], s[12:13], 1.0 op_sel_hi:[1,0,0]
	v_pk_fma_f32 v[8:9], v[8:9], s[12:13], 1.0 op_sel_hi:[1,0,0]
	v_rcp_f32_e32 v4, v4
	v_rcp_f32_e32 v5, v5
	v_rcp_f32_e32 v8, v8
	v_rcp_f32_e32 v9, v9
	v_pk_mul_f32 v[6:7], v[0:1], v[0:1]
	v_pk_mul_f32 v[10:11], v[2:3], v[2:3]
	v_pk_mul_f32 v[6:7], v[6:7], s[62:63] op_sel_hi:[1,0]
	v_pk_fma_f32 v[12:13], v[4:5], s[36:37], v[88:89] op_sel_hi:[1,0,0]
	v_pk_mul_f32 v[10:11], v[10:11], s[62:63] op_sel_hi:[1,0]
	v_exp_f32_e32 v6, v6
	v_exp_f32_e32 v7, v7
	v_pk_fma_f32 v[14:15], v[8:9], s[36:37], v[88:89] op_sel_hi:[1,0,0]
	v_pk_fma_f32 v[12:13], v[4:5], v[12:13], s[38:39] op_sel_hi:[1,1,0]
	v_exp_f32_e32 v10, v10
	v_exp_f32_e32 v11, v11
	v_pk_fma_f32 v[14:15], v[8:9], v[14:15], s[38:39] op_sel_hi:[1,1,0]
	v_pk_fma_f32 v[12:13], v[4:5], v[12:13], s[40:41] op_sel_hi:[1,1,0]
	v_pk_fma_f32 v[14:15], v[8:9], v[14:15], s[40:41] op_sel_hi:[1,1,0]
	v_pk_fma_f32 v[12:13], v[4:5], v[12:13], s[60:61] op_sel_hi:[1,1,0]
	v_pk_fma_f32 v[14:15], v[8:9], v[14:15], s[60:61] op_sel_hi:[1,1,0]
	v_pk_mul_f32 v[4:5], v[4:5], v[12:13]
	v_pk_mul_f32 v[8:9], v[8:9], v[14:15]
	v_pk_mul_f32 v[4:5], v[6:7], v[4:5]
	v_pk_mul_f32 v[6:7], v[10:11], v[8:9]
	v_pk_mul_f32 v[8:9], v[0:1], v[4:5]
	v_pk_fma_f32 v[4:5], v[0:1], v[4:5], v[0:1] neg_lo:[1,0,0] neg_hi:[1,0,0]
	v_cmp_gt_f32_e32 vcc, 0, v1
	v_cmp_gt_f32_e64 s[6:7], 0, v0
	v_pk_mul_f32 v[10:11], v[2:3], v[6:7]
	v_pk_fma_f32 v[6:7], v[2:3], v[6:7], v[2:3] neg_lo:[1,0,0] neg_hi:[1,0,0]
	v_cmp_gt_f32_e64 s[0:1], 0, v2
	v_cmp_gt_f32_e64 s[4:5], 0, v3
	v_cndmask_b32_e64 v0, v4, v8, s[6:7]
	v_cndmask_b32_e32 v1, v5, v9, vcc
	v_cndmask_b32_e64 v2, v6, v10, s[0:1]
	v_cndmask_b32_e64 v3, v7, v11, s[4:5]
	v_mul_f32_e32 v0, v16, v0
	v_mul_f32_e32 v1, v17, v1
	v_mul_f32_e32 v2, v18, v2
	v_mul_f32_e32 v3, v19, v3
	v_cvt_pk_bf16_f32 v0, v0, v1
	v_cvt_pk_bf16_f32 v1, v2, v3
	v_mov_b64_e32 v[252:253], v[0:1]
	s_nop 1
	v_permlane16_swap_b32_e32 v250, v252
	v_permlane16_swap_b32_e32 v251, v253
	s_nop 1
	global_store_dwordx4 v[228:229], v[250:253], off offset:448
	s_cbranch_scc1 .LBB0_696
